# phase starts anchored at 256B; FFN-in phases +56B, others +32B (code placement); early low-prio MFMAs; retention epilogue deferred
# speedup vs baseline: 1.0021x; 1.0021x over previous
.LBB0_141:
	.p2alignl 8, 3212836864
	s_nop 0
	s_nop 0
	s_nop 0
	s_nop 0
	s_nop 0
	s_nop 0
	s_nop 0
	s_nop 0
	s_cmp_lt_i32 s84, 2
	s_cselect_b64 s[4:5], -1, 0
	s_cmp_gt_i32 s85, 1
	s_waitcnt lgkmcnt(0)
	s_cselect_b64 s[6:7], -1, 0
	s_and_b64 s[4:5], s[4:5], s[6:7]
	s_andn2_b64 vcc, exec, s[4:5]
	s_cbranch_vccnz .LBB0_215
	v_lshl_or_b32 v2, s72, 9, v0
	s_mov_b32 s3, 0x28000
	s_mov_b64 s[6:7], s[70:71]
	v_cmp_gt_i32_e32 vcc, s3, v2
	s_and_saveexec_b64 s[4:5], vcc
	s_cbranch_execz .LBB0_161
	s_load_dwordx2 s[8:9], s[6:7], 0xb8
	s_lshl_b32 s3, s33, 9
	s_mov_b64 s[6:7], 0
	s_mov_b32 s14, 0x23fff
	s_movk_i32 s15, 0x7ff
	s_waitcnt lgkmcnt(0)
	s_add_u32 s8, s8, 0x43100000
	s_addc_u32 s9, s9, 0
	v_mov_b32_e32 v5, 0
	s_mov_b32 s16, 0x38e38e39
	s_movk_i32 s17, 0x1fff
	s_movk_i32 s18, 0x37ff
	s_movk_i32 s19, 0x3800
	s_movk_i32 s20, 0x2000
	s_movk_i32 s21, 0x800
	s_mov_b32 s26, 0x27fff
	s_branch .LBB0_146

.LBB0_215:
	.p2alignl 8, 3212836864
	s_nop 0
	s_nop 0
	s_nop 0
	s_nop 0
	s_nop 0
	s_nop 0
	s_nop 0
	s_nop 0
	s_cmp_lt_i32 s84, 3
	s_cselect_b64 s[4:5], -1, 0
	s_cmp_gt_i32 s85, 2
	s_cselect_b64 s[6:7], -1, 0
	s_and_b64 s[4:5], s[4:5], s[6:7]
	s_andn2_b64 vcc, exec, s[4:5]
	s_cbranch_vccnz .LBB0_275
	s_lshl_b32 s3, s72, 6
	s_lshl_b32 s4, s59, 3
	s_add_i32 s4, s3, s4
	s_mov_b64 s[6:7], s[70:71]
	s_mov_b64 s[8:9], s[70:71]
	s_mov_b64 s[10:11], s[70:71]
	s_mov_b64 s[12:13], s[70:71]
	s_mov_b64 s[22:23], s[70:71]
	s_cmpk_gt_i32 s4, 0x3fff
	s_cbranch_scc1 .LBB0_221
	v_mbcnt_lo_u32_b32 v2, -1, 0
	v_mbcnt_hi_u32_b32 v2, -1, v2
	v_and_b32_e32 v3, 64, v2
	v_add_u32_e32 v3, 64, v3
	v_xor_b32_e32 v4, 1, v2
	v_cmp_lt_i32_e32 vcc, v4, v3
	s_load_dwordx2 s[14:15], s[10:11], 0xb8
	s_load_dwordx2 s[18:19], s[6:7], 0x0
	s_load_dwordx2 s[16:17], s[12:13], 0xb8
	s_load_dwordx2 s[20:21], s[8:9], 0x28
	s_load_dwordx2 s[24:25], s[22:23], 0xb8
	v_cndmask_b32_e32 v4, v2, v4, vcc
	v_lshlrev_b32_e32 v82, 2, v4
	v_xor_b32_e32 v4, 2, v2
	v_cmp_lt_i32_e32 vcc, v4, v3
	s_waitcnt lgkmcnt(0)
	s_add_u32 s3, s14, 0x600000
	s_addc_u32 s14, s15, 0
	v_cndmask_b32_e32 v4, v2, v4, vcc
	v_lshlrev_b32_e32 v83, 2, v4
	v_xor_b32_e32 v4, 4, v2
	v_cmp_lt_i32_e32 vcc, v4, v3
	s_add_u32 s15, s16, 0x602000
	s_addc_u32 s16, s17, 0
	v_cndmask_b32_e32 v4, v2, v4, vcc
	v_lshlrev_b32_e32 v84, 2, v4
	v_xor_b32_e32 v4, 8, v2
	v_cmp_lt_i32_e32 vcc, v4, v3
	v_mov_b32_e32 v5, 0
	s_ashr_i32 s5, s4, 31
	v_cndmask_b32_e32 v4, v2, v4, vcc
	v_lshlrev_b32_e32 v85, 2, v4
	v_xor_b32_e32 v4, 16, v2
	v_cmp_lt_i32_e32 vcc, v4, v3
	s_lshl_b32 s6, s33, 6
	v_mov_b32_e32 v9, v5
	v_cndmask_b32_e32 v4, v2, v4, vcc
	v_lshlrev_b32_e32 v86, 2, v4
	v_xor_b32_e32 v4, 32, v2
	v_cmp_lt_i32_e32 vcc, v4, v3
	s_lshl_b64 s[8:9], s[4:5], 13
	s_add_u32 s8, s18, s8
	v_cndmask_b32_e32 v2, v2, v4, vcc
	v_lshlrev_b32_e32 v87, 2, v2
	v_lshlrev_b32_e32 v2, 2, v1
	v_or_b32_e32 v6, 0x400, v2
	v_lshlrev_b32_e32 v8, 2, v6
	v_lshl_add_u64 v[36:37], s[20:21], 0, v[8:9]
	v_or_b32_e32 v8, 0x500, v2
	v_lshlrev_b32_e32 v4, 4, v1
	v_lshlrev_b32_e32 v10, 2, v8
	v_mov_b32_e32 v11, v5
	s_addc_u32 s9, s19, s9
	s_ashr_i32 s7, s6, 31
	v_lshl_add_u64 v[38:39], s[20:21], 0, v[10:11]
	v_or_b32_e32 v10, 0x600, v2
	v_lshl_add_u64 v[44:45], s[8:9], 0, v[4:5]
	s_lshl_b64 s[8:9], s[6:7], 13
	s_lshl_b64 s[10:11], s[4:5], 12
	v_lshlrev_b32_e32 v12, 2, v10
	v_mov_b32_e32 v13, v5
	s_add_u32 s10, s24, s10
	v_lshl_add_u64 v[34:35], s[20:21], 0, v[4:5]
	v_lshl_add_u64 v[40:41], s[20:21], 0, v[12:13]
	v_or_b32_e32 v12, 0x700, v2
	v_lshlrev_b32_e32 v4, 3, v1
	s_addc_u32 s11, s25, s11
	v_lshlrev_b32_e32 v14, 2, v12
	v_mov_b32_e32 v15, v5
	v_lshl_add_u64 v[4:5], s[10:11], 0, v[4:5]
	s_mov_b64 s[10:11], 0x18000800
	v_lshl_add_u64 v[42:43], s[20:21], 0, v[14:15]
	v_lshl_add_u64 v[46:47], v[4:5], 0, s[10:11]
	s_lshl_b64 s[10:11], s[6:7], 12
	v_lshlrev_b32_e32 v88, 2, v2
	v_lshlrev_b32_e32 v89, 2, v6
	v_lshlrev_b32_e32 v90, 2, v8
	v_lshlrev_b32_e32 v91, 2, v10
	v_lshlrev_b32_e32 v92, 2, v12
	s_movk_i32 s5, 0x1000
	v_mov_b32_e32 v93, 0x358637bd
	s_mov_b64 s[12:13], 0x1000

.LBB0_275:
	.p2alignl 8, 3212836864
	s_nop 0
	s_nop 0
	s_nop 0
	s_nop 0
	s_nop 0
	s_nop 0
	s_nop 0
	s_nop 0
	s_nop 0
	s_nop 0
	s_nop 0
	s_nop 0
	s_nop 0
	s_nop 0
	s_cmp_lt_i32 s84, 4
	s_cselect_b64 s[4:5], -1, 0
	s_cmp_gt_i32 s85, 3
	s_cselect_b64 s[6:7], -1, 0
	s_and_b64 s[4:5], s[4:5], s[6:7]
	s_andn2_b64 vcc, exec, s[4:5]
	s_cbranch_vccnz .LBB0_346
	s_mov_b64 s[6:7], s[70:71]
	s_mov_b64 s[8:9], s[70:71]
	s_mov_b64 s[4:5], s[70:71]
	s_cmpk_gt_i32 s2, 0xaff
	v_readfirstlane_b32 s13, v0
	s_cbranch_scc1 .LBB0_292
	s_load_dwordx2 s[10:11], s[6:7], 0xb8
	s_load_dwordx2 s[14:15], s[8:9], 0xb8
	v_lshrrev_b32_e32 v2, 5, v0
	v_lshrrev_b32_e32 v4, 1, v0
	v_and_b32_e32 v2, 4, v2
	v_bfe_u32 v3, v0, 2, 2
	v_and_b32_e32 v13, 24, v4
	s_waitcnt lgkmcnt(0)
	s_add_u32 s40, s10, 0x18000000
	v_or3_b32 v2, v2, v3, v13
	v_lshlrev_b32_e32 v3, 4, v0
	s_addc_u32 s41, s11, 0
	v_or_b32_e32 v10, 0x2000, v3
	s_add_u32 s42, s14, 0x2400000
	v_lshrrev_b32_e32 v4, 7, v10
	s_movk_i32 s6, 0x60
	s_addc_u32 s43, s15, 0
	v_and_or_b32 v5, v4, s6, v2
	v_bfe_u32 v14, v0, 2, 4
	s_movk_i32 s6, 0x70
	s_ashr_i32 s45, s2, 31
	v_and_or_b32 v4, v4, s6, v14
	s_lshr_b32 s6, s45, 29
	s_add_i32 s6, s2, s6
	s_lshr_b32 s3, s13, 6
	s_ashr_i32 s7, s6, 3
	s_and_b32 s6, s6, -8
	s_lshr_b32 s14, s13, 8
	s_lshl_b32 s44, s3, 10
	s_sub_i32 s6, s2, s6
	s_cmp_lt_i32 s6, 0
	s_movk_i32 s46, 0x161
	s_cselect_b32 s8, s46, 0x160
	s_mul_i32 s6, s6, s8
	s_add_i32 s6, s6, s7
	s_mul_hi_i32 s7, s6, 0x2e8ba2e9
	s_lshr_b32 s8, s7, 31
	s_ashr_i32 s7, s7, 6
	s_add_i32 s7, s7, s8
	s_lshl_b32 s8, s7, 3
	s_mulk_i32 s7, 0x160
	s_sub_i32 s6, s6, s7
	s_sext_i32_i16 s7, s6
	s_bfe_u32 s7, s7, 0x3001c
	s_add_i32 s7, s6, s7
	s_sext_i32_i16 s9, s7
	s_and_b32 s7, s7, 0xfff8
	s_sub_i32 s6, s6, s7
	s_sext_i32_i16 s6, s6
	v_and_b32_e32 v6, 32, v0
	s_lshr_b32 s12, s9, 3
	s_add_i32 s30, s8, s6
	v_bitop3_b32 v11, v3, v6, 48 bitop3:0x6c
	v_and_b32_e32 v12, 64, v0
	s_ashr_i32 s31, s30, 31
	s_bfe_i64 s[8:9], s[12:13], 0x100000
	v_or_b32_e32 v3, v11, v12
	s_lshl_b64 s[6:7], s[30:31], 20
	s_lshl_b64 s[8:9], s[8:9], 20
	v_lshl_or_b32 v132, v4, 12, v3
	v_lshrrev_b32_e32 v4, 3, v0
	s_add_u32 s36, s42, s8
	v_and_or_b32 v2, v4, 32, v2
	s_addc_u32 s37, s43, s9
	s_add_i32 s31, s44, 0
	v_lshl_or_b32 v134, v2, 12, v3
	s_add_i32 m0, s31, 0x10000
	v_lshl_or_b32 v130, v5, 12, v3
	global_load_lds_dwordx4 v134, s[36:37]
	s_add_i32 m0, s31, 0x12000
	s_add_u32 s8, s36, 0x80000
	global_load_lds_dwordx4 v130, s[36:37]
	s_addc_u32 s9, s37, 0
	s_add_i32 m0, s31, 0x14000
	v_and_or_b32 v2, v4, 48, v14
	global_load_lds_dwordx4 v134, s[8:9]
	s_add_i32 m0, s31, 0x16000
	s_add_u32 s34, s40, s6
	s_addc_u32 s35, s41, s7
	s_add_i32 s47, s31, 0x2000
	v_lshl_or_b32 v136, v2, 12, v3
	global_load_lds_dwordx4 v130, s[8:9]
	s_mov_b32 m0, s31
	s_add_u32 s6, s34, 0x80000
	global_load_lds_dwordx4 v136, s[34:35]
	s_mov_b32 m0, s47
	s_addc_u32 s7, s35, 0
	s_add_i32 s48, s31, 0x4000
	global_load_lds_dwordx4 v132, s[34:35]
	s_mov_b32 m0, s48
	s_add_i32 s49, s31, 0x6000
	global_load_lds_dwordx4 v136, s[6:7]
	s_mov_b32 m0, s49
	s_load_dwordx2 s[4:5], s[4:5], 0xb8
	global_load_lds_dwordx4 v132, s[6:7]
	v_mov_b32_e32 v135, 0
	v_mov_b32_e32 v131, v135
	v_mov_b32_e32 v137, v135
	v_mov_b32_e32 v133, v135
	s_cmp_eq_u32 s14, 1
	s_mov_b32 s50, 0
	v_lshl_add_u64 v[8:9], s[36:37], 0, v[134:135]
	v_lshl_add_u64 v[6:7], s[36:37], 0, v[130:131]
	v_lshl_add_u64 v[2:3], s[34:35], 0, v[136:137]
	s_cselect_b64 s[6:7], -1, 0
	s_cmp_lg_u32 s14, 1
	v_lshl_add_u64 v[4:5], s[34:35], 0, v[132:133]
	s_cbranch_scc1 .LBB0_279
	s_barrier

.LBB0_346:
	.p2alignl 8, 3212836864
	s_nop 0
	s_nop 0
	s_nop 0
	s_nop 0
	s_nop 0
	s_nop 0
	s_nop 0
	s_nop 0
	s_cmp_lt_i32 s84, 5
	s_cselect_b64 s[4:5], -1, 0
	s_cmp_gt_i32 s85, 4
	s_cselect_b64 s[6:7], -1, 0
	s_and_b64 s[4:5], s[4:5], s[6:7]
	s_andn2_b64 vcc, exec, s[4:5]
	s_cbranch_vccnz .LBB0_453
	s_and_b32 s3, s2, 7
	s_ashr_i32 s14, s33, 6
	s_mul_i32 s48, s14, s3
	s_ashr_i32 s3, s2, 6
	s_add_i32 s48, s48, s3
	s_mov_b64 s[8:9], s[70:71]
	s_mov_b64 s[34:35], s[70:71]
	s_mov_b64 s[4:5], s[70:71]
	s_mov_b64 s[6:7], s[70:71]
	s_mov_b64 s[10:11], s[70:71]
	s_mov_b64 s[12:13], s[70:71]
	s_mov_b64 s[22:23], s[70:71]
	s_mov_b64 s[24:25], s[70:71]
	s_mov_b64 s[26:27], s[70:71]
	s_mov_b64 s[28:29], s[70:71]
	s_mov_b64 s[30:31], s[70:71]
	s_cmp_gt_i32 s48, 63
	v_readfirstlane_b32 s14, v0
	s_cbranch_scc1 .LBB0_399
	v_lshrrev_b32_e32 v2, 5, v0
	v_lshrrev_b32_e32 v4, 1, v0
	v_and_b32_e32 v2, 4, v2
	v_bfe_u32 v3, v0, 2, 2
	v_and_b32_e32 v4, 24, v4
	v_lshlrev_b32_e32 v210, 4, v0
	v_or3_b32 v2, v2, v3, v4
	v_bfe_u32 v3, v0, 3, 25
	v_and_b32_e32 v5, 32, v0
	s_load_dwordx2 s[16:17], s[8:9], 0xb8
	s_load_dwordx2 s[18:19], s[34:35], 0xb8
	v_or_b32_e32 v3, 64, v3
	s_movk_i32 s8, 0x60
	v_bitop3_b32 v10, v210, v5, 48 bitop3:0x6c
	v_and_b32_e32 v11, 64, v0
	v_and_or_b32 v4, v3, s8, v2
	v_or_b32_e32 v5, v10, v11
	v_mul_u32_u24_e32 v4, 0x1600, v4
	v_lshrrev_b32_e32 v5, 1, v5
	v_or_b32_e32 v4, v4, v5
	v_lshlrev_b32_e32 v146, 1, v4
	v_bfe_u32 v4, v0, 2, 4
	s_movk_i32 s8, 0x70
	s_waitcnt lgkmcnt(0)
	s_add_u32 s49, s16, 0x20000000
	v_and_or_b32 v3, v3, s8, v4
	s_addc_u32 s50, s17, 0
	s_lshr_b32 s17, s14, 6
	s_bfe_u32 s15, s2, 0x30003
	v_mul_u32_u24_e32 v12, 0x1600, v3
	s_lshr_b32 s16, s14, 8
	s_lshl_b32 s3, s17, 10
	v_or_b32_e32 v3, v12, v5
	s_mul_i32 s8, s15, 0x2c0000
	v_lshlrev_b32_e32 v148, 1, v3
	v_lshrrev_b32_e32 v3, 3, v0
	s_add_u32 s18, s18, s8
	v_and_or_b32 v2, v3, 32, v2
	s_addc_u32 s19, s19, 0
	v_mul_u32_u24_e32 v2, 0x1600, v2
	s_add_u32 s8, s18, 0xd400000
	v_or_b32_e32 v2, v2, v5
	s_addc_u32 s9, s19, 0
	s_add_i32 s51, s3, 0
	v_lshlrev_b32_e32 v150, 1, v2
	s_add_i32 m0, s51, 0x10000
	v_and_or_b32 v2, v3, 48, v4
	global_load_lds_dwordx4 v150, s[8:9]
	s_add_i32 m0, s51, 0x12000
	s_add_u32 s18, s18, 0xd560000
	global_load_lds_dwordx4 v146, s[8:9]
	s_addc_u32 s19, s19, 0
	s_add_i32 m0, s51, 0x14000
	s_mul_i32 s21, s48, 0x2c0000
	global_load_lds_dwordx4 v150, s[18:19]
	s_add_i32 m0, s51, 0x16000
	v_mul_u32_u24_e32 v13, 0x1600, v2
	s_mul_hi_i32 s20, s48, 0x2c0000
	s_add_u32 s34, s49, s21
	v_or_b32_e32 v2, v5, v13
	s_addc_u32 s35, s50, s20
	s_add_i32 s52, s51, 0x2000
	v_lshlrev_b32_e32 v152, 1, v2
	global_load_lds_dwordx4 v146, s[18:19]
	s_mov_b32 m0, s51
	s_add_u32 s18, s34, 0x160000
	global_load_lds_dwordx4 v152, s[34:35]
	s_mov_b32 m0, s52
	s_addc_u32 s19, s35, 0
	s_add_i32 s53, s51, 0x4000
	global_load_lds_dwordx4 v148, s[34:35]
	s_mov_b32 m0, s53
	s_add_i32 s54, s51, 0x6000
	global_load_lds_dwordx4 v152, s[18:19]
	s_mov_b32 m0, s54
	v_mov_b32_e32 v151, 0
	global_load_lds_dwordx4 v148, s[18:19]
	s_load_dwordx2 s[40:41], s[4:5], 0x0
	s_load_dwordx2 s[36:37], s[6:7], 0xb0
	s_load_dwordx2 s[42:43], s[10:11], 0xb8
	s_nop 0
	s_load_dwordx2 s[6:7], s[12:13], 0xb8
	s_load_dwordx2 s[4:5], s[22:23], 0xb8
	s_load_dwordx2 s[10:11], s[24:25], 0xb8
	s_load_dwordx2 s[38:39], s[26:27], 0xb8
	s_nop 0
	s_load_dwordx2 s[28:29], s[28:29], 0xb8
	s_nop 0
	s_load_dwordx2 s[26:27], s[30:31], 0xb8
	v_mov_b32_e32 v147, v151
	v_mov_b32_e32 v153, v151
	v_mov_b32_e32 v149, v151
	s_cmp_eq_u32 s16, 1
	s_mov_b32 s55, 0
	v_lshl_add_u64 v[8:9], s[8:9], 0, v[150:151]
	v_lshl_add_u64 v[6:7], s[8:9], 0, v[146:147]
	v_lshl_add_u64 v[2:3], s[34:35], 0, v[152:153]
	s_cselect_b64 s[12:13], -1, 0
	s_cmp_lg_u32 s16, 1
	v_lshl_add_u64 v[4:5], s[34:35], 0, v[148:149]
	s_cbranch_scc1 .LBB0_350
	s_barrier

.LBB0_453:
	.p2alignl 8, 3212836864
	s_nop 0
	s_nop 0
	s_nop 0
	s_nop 0
	s_nop 0
	s_nop 0
	s_nop 0
	s_nop 0
	s_cmp_lt_i32 s84, 7
	s_cselect_b64 s[4:5], -1, 0
	s_cmp_gt_i32 s85, 6
	s_cselect_b64 s[6:7], -1, 0
	s_and_b64 s[4:5], s[4:5], s[6:7]
	s_andn2_b64 vcc, exec, s[4:5]
	s_cbranch_vccnz .LBB0_562
	s_cmpk_lt_i32 s2, 0xc00
	s_mov_b64 s[26:27], s[70:71]
	s_mov_b64 s[28:29], s[70:71]
	s_mov_b64 s[4:5], s[70:71]
	s_mov_b64 s[8:9], s[70:71]
	s_mov_b64 s[10:11], s[70:71]
	s_mov_b64 s[12:13], s[70:71]
	s_mov_b64 s[22:23], s[70:71]
	s_mov_b64 s[24:25], s[70:71]
	s_cselect_b64 s[30:31], -1, 0
	s_cmpk_gt_i32 s2, 0xbff
	v_readfirstlane_b32 s3, v0
	s_cbranch_scc0 .LBB0_457
	s_andn2_b64 vcc, exec, s[30:31]
	s_cbranch_vccz .LBB0_458

.LBB0_562:
	.p2alignl 8, 3212836864
	s_nop 0
	s_nop 0
	s_nop 0
	s_nop 0
	s_nop 0
	s_nop 0
	s_nop 0
	s_nop 0
	s_cmp_lt_i32 s84, 8
	s_cselect_b64 s[4:5], -1, 0
	s_cmp_gt_i32 s85, 7
	s_cselect_b64 s[6:7], -1, 0
	s_and_b64 s[4:5], s[4:5], s[6:7]
	s_andn2_b64 vcc, exec, s[4:5]
	s_cbranch_vccnz .LBB0_633
	s_mov_b64 s[4:5], s[70:71]
	s_mov_b64 s[6:7], s[70:71]
	s_mov_b64 s[8:9], s[70:71]
	s_mov_b64 s[10:11], s[70:71]
	s_mov_b64 s[12:13], s[70:71]
	s_cmpk_gt_i32 s72, 0xff
	s_cbranch_scc1 .LBB0_579
	s_load_dwordx2 s[26:27], s[4:5], 0xb8
	s_load_dwordx2 s[30:31], s[6:7], 0xb8
	s_load_dwordx2 s[36:37], s[8:9], 0xb8
	s_load_dwordx2 s[28:29], s[10:11], 0xb8
	s_load_dwordx2 s[34:35], s[12:13], 0xb8
	s_waitcnt lgkmcnt(0)
	s_add_u32 s10, s26, 0x20000000
	s_addc_u32 s11, s27, 0
	s_add_u32 s12, s30, 0x24000000
	s_addc_u32 s13, s31, 0
	s_add_u32 s22, s36, 0x2b000000
	s_addc_u32 s23, s37, 0
	s_lshr_b32 s4, s58, 8
	v_and_b32_e32 v2, 15, v0
	s_lshl_b32 s7, s4, 5
	s_movk_i32 s6, 0x210
	v_or_b32_e32 v6, s7, v2
	s_bfe_u32 s3, s58, 0x20006
	v_mul_lo_u32 v6, v6, s6
	s_add_i32 s14, 0, 0x10800
	v_lshrrev_b32_e32 v3, 4, v1
	s_lshl_b32 s5, s3, 4
	v_add_u32_e32 v10, 0, v6
	v_mov_b32_e32 v6, s14
	v_bfe_u32 v4, v0, 2, 2
	v_or_b32_e32 v5, s5, v2
	v_mad_u32_u24 v2, v2, s6, v6
	v_lshl_or_b32 v6, v3, 2, s7
	v_or_b32_e32 v7, v6, v4
	s_movk_i32 s7, 0x110
	v_mul_lo_u32 v7, v7, s7
	s_add_i32 s8, 0, 0x18c00
	v_lshlrev_b32_e32 v3, 3, v3
	v_lshrrev_b32_e32 v104, 3, v0
	v_add_u32_e32 v22, 1, v5
	v_add_u32_e32 v12, s8, v7
	v_lshlrev_b32_e32 v7, 3, v0
	v_or_b32_e32 v4, v3, v4
	v_cvt_f32_ubyte0_e32 v103, v22
	v_xor_b32_e32 v22, 63, v104
	v_and_b32_e32 v13, 24, v7
	v_mul_u32_u24_e32 v7, 0x210, v4
	v_cvt_f32_ubyte0_e32 v105, v22
	v_sub_u32_e32 v22, v5, v6
	v_add3_u32 v14, 0, v7, v13
	v_mov_b32_e32 v7, s8
	v_sub_u32_e32 v23, 0, v22
	v_mad_u32_u24 v15, v4, s7, v7
	v_mad_u32_u24 v20, v104, s7, v7
	v_bitop3_b32 v7, s5, v0, 15 bitop3:7
	v_max_i32_e32 v23, v22, v23
	v_add_u32_e32 v23, v23, v7
	v_xad_u32 v6, v6, -1, v5
	v_cvt_f32_i32_e32 v146, v23
	v_sub_u32_e32 v23, 0, v6
	v_max_i32_e32 v6, v6, v23
	v_add_u32_e32 v6, v6, v7
	v_cvt_f32_i32_e32 v147, v6
	v_add_u32_e32 v6, -2, v22
	v_sub_u32_e32 v23, 2, v22
	v_max_i32_e32 v6, v6, v23
	v_add_u32_e32 v6, v6, v7
	v_cvt_f32_i32_e32 v148, v6
	v_add_u32_e32 v6, -3, v22
	v_sub_u32_e32 v23, 3, v22
	v_max_i32_e32 v6, v6, v23
	v_add_u32_e32 v6, v6, v7
	v_cvt_f32_i32_e32 v149, v6
	v_add_u32_e32 v6, -16, v22
	v_sub_u32_e32 v23, 16, v22
	v_max_i32_e32 v6, v6, v23
	v_add_u32_e32 v6, v6, v7
	v_cvt_f32_i32_e32 v150, v6
	v_subrev_u32_e32 v6, 17, v22
	v_sub_u32_e32 v23, 17, v22
	v_max_i32_e32 v6, v6, v23
	v_add_u32_e32 v6, v6, v7
	v_cvt_f32_i32_e32 v151, v6
	v_subrev_u32_e32 v6, 18, v22
	v_sub_u32_e32 v23, 18, v22
	v_max_i32_e32 v6, v6, v23
	v_add_u32_e32 v6, v6, v7
	v_and_b32_e32 v9, 48, v0
	s_and_b32 s17, s58, 0xffffffc0
	v_and_b32_e32 v4, 7, v0
	v_cvt_f32_i32_e32 v152, v6
	v_subrev_u32_e32 v6, 19, v22
	v_sub_u32_e32 v22, 19, v22
	v_add_u32_e32 v11, v2, v9
	v_add_u32_e32 v16, s17, v2
	v_and_b32_e32 v2, 31, v0
	v_lshlrev_b32_e32 v21, 4, v4
	v_max_i32_e32 v6, v6, v22
	v_lshrrev_b32_e32 v102, 5, v0
	v_lshlrev_b32_e32 v19, 4, v2
	v_mov_b32_e32 v107, 0
	v_add_u32_e32 v6, v6, v7
	v_lshl_or_b32 v106, v104, 13, v21
	v_cvt_f32_i32_e32 v153, v6
	v_lshl_add_u64 v[6:7], s[36:37], 0, v[106:107]
	v_lshl_or_b32 v106, v102, 12, v19
	s_lshl_b32 s3, s3, 12
	v_lshl_add_u32 v155, v0, 4, s14
	s_mov_b64 s[14:15], 0x2b100000
	v_lshl_add_u64 v[110:111], s[26:27], 0, v[106:107]
	v_lshl_add_u64 v[112:113], s[30:31], 0, v[106:107]
	v_lshlrev_b32_e32 v106, 9, v5
	s_add_i32 s3, s3, 0
	v_lshl_add_u64 v[108:109], v[6:7], 0, s[14:15]
	v_lshl_add_u64 v[6:7], s[34:35], 0, v[106:107]
	s_mov_b64 s[14:15], 0x1b00000
	s_and_b32 s16, s58, 0xffffff00
	s_add_i32 s3, s3, 0x1d000
	v_lshl_add_u64 v[114:115], v[6:7], 0, s[14:15]
	v_lshrrev_b32_e32 v6, 1, v9
	v_lshlrev_b32_e32 v2, 3, v2
	s_cmp_eq_u32 s4, 1
	v_lshl_or_b32 v106, v5, 13, v6
	v_mad_u32_u24 v8, v5, s6, 0
	v_lshlrev_b32_e32 v17, 2, v1
	v_mad_u32_u24 v18, v102, s6, 0
	v_lshlrev_b32_e32 v4, 3, v4
	s_cselect_b64 s[4:5], -1, 0
	s_cmpk_lt_u32 s58, 0x100
	v_lshl_add_u64 v[6:7], s[28:29], 0, v[106:107]
	s_mov_b64 s[14:15], 0x3b000040
	v_lshlrev_b32_e32 v106, 1, v2
	v_mbcnt_lo_u32_b32 v2, -1, 0
	s_mov_b32 s25, 0
	s_cselect_b64 s[6:7], -1, 0
	v_cmp_gt_u32_e64 s[8:9], 16, v1
	v_or_b32_e32 v154, 0xfffffe00, v0
	v_lshl_add_u64 v[116:117], v[6:7], 0, s[14:15]
	s_mov_b32 s14, 0xc2fc0000
	s_mov_b32 s15, 0x800000
	s_movk_i32 s20, 0x63f
	s_mov_b32 s21, 0x10000
	s_mov_b32 s36, 0x20000
	s_mov_b32 s37, 0x30000
	v_lshlrev_b32_e32 v118, 1, v4
	s_mov_b32 s38, 0x40000
	s_mov_b32 s39, 0x50000
	s_mov_b32 s40, 0x60000
	s_mov_b32 s41, 0x70000
	s_mov_b32 s42, 0x80000
	v_add_u32_e32 v156, v8, v9
	v_add_u32_e32 v157, v10, v9
	v_add_u32_e32 v158, s16, v11
	v_add_u32_e32 v159, v12, v13
	v_add_u32_e32 v160, s17, v14
	v_add_u32_e32 v161, v15, v13
	v_add_u32_e32 v163, v16, v3
	s_mov_b64 s[26:27], 0x80000
	s_mov_b64 s[28:29], 0x8000
	v_mov_b32_e32 v164, 0x42800000
	v_mov_b32_e32 v165, 0x42000000
	v_mov_b32_e32 v172, v107
	v_mov_b32_e32 v173, v107
	v_mov_b32_e32 v174, v107
	v_mov_b32_e32 v175, v107
	v_not_b32_e32 v166, 63
	v_add_u32_e32 v167, v18, v19
	v_add_u32_e32 v168, v20, v21
	v_add_u32_e32 v169, s3, v17
	v_mbcnt_hi_u32_b32 v170, -1, v2
	v_xor_b32_e32 v240, 16, v170
	v_xor_b32_e32 v241, 32, v170
	v_lshlrev_b32_e32 v240, 2, v240
	v_lshlrev_b32_e32 v241, 2, v241
	s_mov_b32 s43, s72
	s_branch .LBB0_566

.LBB0_633:
	.p2alignl 8, 3212836864
	s_nop 0
	s_nop 0
	s_nop 0
	s_nop 0
	s_nop 0
	s_nop 0
	s_nop 0
	s_nop 0
	s_cmp_lt_i32 s84, 9
	s_cselect_b64 s[4:5], -1, 0
	s_cmp_gt_i32 s85, 8
	s_cselect_b64 s[6:7], -1, 0
	s_and_b64 s[4:5], s[4:5], s[6:7]
	s_andn2_b64 vcc, exec, s[4:5]
	s_cbranch_vccnz .LBB0_691
	s_lshl_b32 s3, s72, 3
	s_add_i32 s4, s3, s59
	s_mov_b64 s[6:7], s[70:71]
	s_mov_b64 s[8:9], s[70:71]
	s_mov_b64 s[10:11], s[70:71]
	s_mov_b64 s[12:13], s[70:71]
	s_cmpk_gt_i32 s4, 0x3fff
	s_cbranch_scc1 .LBB0_637
	s_load_dwordx2 s[14:15], s[6:7], 0xb8
	s_load_dwordx2 s[16:17], s[8:9], 0xb8
	s_load_dwordx2 s[18:19], s[12:13], 0x48
	s_load_dwordx2 s[20:21], s[10:11], 0xb8
	s_ashr_i32 s5, s4, 31
	s_lshl_b32 s6, s33, 3
	s_lshl_b64 s[12:13], s[4:5], 13
	s_waitcnt lgkmcnt(0)
	s_add_u32 s8, s16, s12
	s_addc_u32 s9, s17, s13
	s_ashr_i32 s7, s6, 31
	v_lshlrev_b32_e32 v50, 5, v1
	v_mov_b32_e32 v51, 0
	s_lshl_b64 s[10:11], s[6:7], 13
	v_or_b32_e32 v2, 0x1000, v50
	v_mov_b32_e32 v3, v51
	s_add_u32 s12, s14, s12
	v_lshl_add_u64 v[54:55], s[18:19], 0, v[2:3]
	v_or_b32_e32 v2, 0x1800, v50
	s_addc_u32 s13, s15, s13
	s_lshl_b64 s[14:15], s[4:5], 9
	v_lshl_add_u64 v[56:57], s[18:19], 0, v[2:3]
	v_or_b32_e32 v2, 0x2000, v50
	s_add_u32 s3, s20, s14
	v_lshl_add_u64 v[58:59], s[18:19], 0, v[2:3]
	v_or_b32_e32 v2, 0x2800, v50
	s_addc_u32 s5, s21, s15
	v_lshl_add_u64 v[52:53], s[18:19], 0, v[50:51]
	v_lshl_add_u64 v[60:61], s[18:19], 0, v[2:3]
	v_or_b32_e32 v2, 0x3000, v50
	v_or_b32_e32 v50, 0x3800, v50
	s_add_u32 s22, s3, 0x1b00000
	v_lshl_add_u64 v[62:63], s[18:19], 0, v[2:3]
	v_lshl_add_u64 v[64:65], s[18:19], 0, v[50:51]
	v_lshlrev_b32_e32 v50, 4, v1
	s_addc_u32 s23, s5, 0
	s_lshl_b64 s[24:25], s[6:7], 9
	s_mov_b32 s26, 0x3b000000
	s_mov_b32 s3, 0x33000000
	s_mov_b32 s5, 0x3b001000
	s_mov_b32 s7, 0x33001000

.LBB0_691:
	.p2alignl 8, 3212836864
	s_nop 0
	s_nop 0
	s_nop 0
	s_nop 0
	s_nop 0
	s_nop 0
	s_nop 0
	s_nop 0
	s_cmp_lt_i32 s84, 10
	s_cselect_b64 s[4:5], -1, 0
	s_cmp_gt_i32 s85, 9
	s_cselect_b64 s[6:7], -1, 0
	s_and_b64 s[4:5], s[4:5], s[6:7]
	s_andn2_b64 vcc, exec, s[4:5]
	s_cbranch_vccnz .LBB0_796
	s_and_b32 s3, s2, 7
	s_ashr_i32 s8, s33, 6
	s_mul_i32 s3, s8, s3
	s_ashr_i32 s8, s2, 6
	s_add_i32 s8, s3, s8
	s_mov_b64 s[10:11], s[70:71]
	s_mov_b64 s[12:13], s[70:71]
	s_mov_b64 s[4:5], s[70:71]
	s_mov_b64 s[6:7], s[70:71]
	s_mov_b64 s[22:23], s[70:71]
	s_mov_b64 s[24:25], s[70:71]
	s_mov_b64 s[26:27], s[70:71]
	s_mov_b64 s[28:29], s[70:71]
	s_mov_b64 s[30:31], s[70:71]
	s_mov_b64 s[34:35], s[70:71]
	s_mov_b64 s[36:37], s[70:71]
	s_cmp_gt_i32 s8, 63
	v_readfirstlane_b32 s3, v0
	s_cbranch_scc1 .LBB0_742
	s_load_dwordx2 s[14:15], s[10:11], 0xb8
	s_load_dwordx2 s[18:19], s[12:13], 0xb8
	v_lshlrev_b32_e32 v210, 4, v0
	v_lshrrev_b32_e32 v2, 5, v0
	v_lshrrev_b32_e32 v4, 1, v0
	v_and_b32_e32 v2, 4, v2
	v_bfe_u32 v3, v0, 2, 2
	v_and_b32_e32 v4, 24, v4
	v_or_b32_e32 v10, 0x2000, v210
	v_or3_b32 v2, v2, v3, v4
	v_lshrrev_b32_e32 v3, 7, v10
	s_movk_i32 s9, 0x60
	s_waitcnt lgkmcnt(0)
	s_add_u32 s52, s14, 0x33000000
	v_and_or_b32 v4, v3, s9, v2
	v_bfe_u32 v13, v0, 2, 4
	s_movk_i32 s9, 0x70
	s_addc_u32 s53, s15, 0
	s_lshr_b32 s16, s3, 6
	s_bfe_u32 s14, s2, 0x30003
	v_and_or_b32 v3, v3, s9, v13
	s_ashr_i32 s9, s8, 31
	s_lshr_b32 s15, s3, 8
	s_lshl_b32 s54, s16, 10
	v_and_b32_e32 v5, 32, v0
	s_lshl_b64 s[12:13], s[8:9], 21
	s_lshl_b32 s9, s14, 21
	v_bitop3_b32 v11, v210, v5, 48 bitop3:0x6c
	v_and_b32_e32 v12, 64, v0
	s_add_u32 s17, s18, s9
	v_or_b32_e32 v5, v11, v12
	s_addc_u32 s19, s19, 0
	v_lshl_or_b32 v148, v3, 13, v5
	v_lshrrev_b32_e32 v3, 3, v0
	s_add_u32 s10, s17, 0x15c00000
	v_and_or_b32 v2, v3, 32, v2
	s_addc_u32 s11, s19, 0
	s_add_i32 s9, s54, 0
	v_lshl_or_b32 v150, v2, 13, v5
	s_add_i32 m0, s9, 0x10000
	v_lshl_or_b32 v146, v4, 13, v5
	global_load_lds_dwordx4 v150, s[10:11]
	s_add_i32 m0, s9, 0x12000
	s_add_u32 s18, s17, 0x15d00000
	global_load_lds_dwordx4 v146, s[10:11]
	s_addc_u32 s19, s19, 0
	s_add_i32 m0, s9, 0x14000
	v_and_or_b32 v2, v3, 48, v13
	global_load_lds_dwordx4 v150, s[18:19]
	s_add_i32 m0, s9, 0x16000
	s_add_u32 s12, s52, s12
	s_addc_u32 s13, s53, s13
	s_add_i32 s55, s9, 0x2000
	v_lshl_or_b32 v152, v2, 13, v5
	global_load_lds_dwordx4 v146, s[18:19]
	s_mov_b32 m0, s9
	s_add_u32 s18, s12, 0x100000
	global_load_lds_dwordx4 v152, s[12:13]
	s_mov_b32 m0, s55
	s_addc_u32 s19, s13, 0
	s_add_i32 s56, s9, 0x4000
	global_load_lds_dwordx4 v148, s[12:13]
	s_mov_b32 m0, s56
	s_add_i32 s57, s9, 0x6000
	global_load_lds_dwordx4 v152, s[18:19]
	s_mov_b32 m0, s57
	v_mov_b32_e32 v151, 0
	global_load_lds_dwordx4 v148, s[18:19]
	s_load_dwordx2 s[42:43], s[4:5], 0xb0
	s_load_dwordx2 s[38:39], s[6:7], 0xb0
	s_load_dwordx2 s[44:45], s[22:23], 0xb8
	s_nop 0
	s_load_dwordx2 s[6:7], s[24:25], 0xb8
	s_load_dwordx2 s[4:5], s[26:27], 0xb8
	s_load_dwordx2 s[22:23], s[28:29], 0xb8
	s_load_dwordx2 s[40:41], s[30:31], 0xb8
	s_nop 0
	s_load_dwordx2 s[34:35], s[34:35], 0xb8
	s_nop 0
	s_load_dwordx2 s[30:31], s[36:37], 0xb8
	v_mov_b32_e32 v147, v151
	v_mov_b32_e32 v153, v151
	v_mov_b32_e32 v149, v151
	s_cmp_eq_u32 s15, 1
	s_mov_b32 s60, 0
	v_lshl_add_u64 v[8:9], s[10:11], 0, v[150:151]
	v_lshl_add_u64 v[6:7], s[10:11], 0, v[146:147]
	v_lshl_add_u64 v[2:3], s[12:13], 0, v[152:153]
	s_cselect_b64 s[24:25], -1, 0
	s_cmp_lg_u32 s15, 1
	v_lshl_add_u64 v[4:5], s[12:13], 0, v[148:149]
	s_cbranch_scc1 .LBB0_695
	s_barrier

.LBB0_796:
	.p2alignl 8, 3212836864
	s_nop 0
	s_nop 0
	s_nop 0
	s_nop 0
	s_nop 0
	s_nop 0
	s_nop 0
	s_nop 0
	s_nop 0
	s_nop 0
	s_nop 0
	s_nop 0
	s_nop 0
	s_nop 0
	s_cmp_lt_i32 s84, 12
	s_cselect_b64 s[4:5], -1, 0
	s_cmp_gt_i32 s85, 11
	s_cselect_b64 s[6:7], -1, 0
	s_and_b64 s[4:5], s[4:5], s[6:7]
	s_andn2_b64 vcc, exec, s[4:5]
	s_cbranch_vccnz .LBB0_867
	s_mov_b64 s[6:7], s[70:71]
	s_mov_b64 s[8:9], s[70:71]
	s_mov_b64 s[4:5], s[70:71]
	s_cmpk_gt_i32 s2, 0xaff
	v_readfirstlane_b32 s13, v0
	s_cbranch_scc1 .LBB0_813
	s_load_dwordx2 s[10:11], s[6:7], 0xb8
	s_load_dwordx2 s[14:15], s[8:9], 0xb8
	v_lshrrev_b32_e32 v2, 5, v0
	v_lshrrev_b32_e32 v4, 1, v0
	v_and_b32_e32 v2, 4, v2
	v_bfe_u32 v3, v0, 2, 2
	v_and_b32_e32 v13, 24, v4
	s_waitcnt lgkmcnt(0)
	s_add_u32 s40, s10, 0x18000000
	v_or3_b32 v2, v2, v3, v13
	v_lshlrev_b32_e32 v3, 4, v0
	s_addc_u32 s41, s11, 0
	v_or_b32_e32 v10, 0x2000, v3
	s_add_u32 s42, s14, 0x5000000
	v_lshrrev_b32_e32 v4, 7, v10
	s_movk_i32 s6, 0x60
	s_addc_u32 s43, s15, 0
	v_and_or_b32 v5, v4, s6, v2
	v_bfe_u32 v14, v0, 2, 4
	s_movk_i32 s6, 0x70
	s_ashr_i32 s45, s2, 31
	v_and_or_b32 v4, v4, s6, v14
	s_lshr_b32 s6, s45, 29
	s_add_i32 s6, s2, s6
	s_lshr_b32 s3, s13, 6
	s_ashr_i32 s7, s6, 3
	s_and_b32 s6, s6, -8
	s_lshr_b32 s14, s13, 8
	s_lshl_b32 s44, s3, 10
	s_sub_i32 s6, s2, s6
	s_cmp_lt_i32 s6, 0
	s_movk_i32 s46, 0x161
	s_cselect_b32 s8, s46, 0x160
	s_mul_i32 s6, s6, s8
	s_add_i32 s6, s6, s7
	s_mul_hi_i32 s7, s6, 0x2e8ba2e9
	s_lshr_b32 s8, s7, 31
	s_ashr_i32 s7, s7, 6
	s_add_i32 s7, s7, s8
	s_lshl_b32 s8, s7, 3
	s_mulk_i32 s7, 0x160
	s_sub_i32 s6, s6, s7
	s_sext_i32_i16 s7, s6
	s_bfe_u32 s7, s7, 0x3001c
	s_add_i32 s7, s6, s7
	s_sext_i32_i16 s9, s7
	s_and_b32 s7, s7, 0xfff8
	s_sub_i32 s6, s6, s7
	s_sext_i32_i16 s6, s6
	v_and_b32_e32 v6, 32, v0
	s_lshr_b32 s12, s9, 3
	s_add_i32 s30, s8, s6
	v_bitop3_b32 v11, v3, v6, 48 bitop3:0x6c
	v_and_b32_e32 v12, 64, v0
	s_ashr_i32 s31, s30, 31
	s_bfe_i64 s[8:9], s[12:13], 0x100000
	v_or_b32_e32 v3, v11, v12
	s_lshl_b64 s[6:7], s[30:31], 20
	s_lshl_b64 s[8:9], s[8:9], 20
	v_lshl_or_b32 v132, v4, 12, v3
	v_lshrrev_b32_e32 v4, 3, v0
	s_add_u32 s36, s42, s8
	v_and_or_b32 v2, v4, 32, v2
	s_addc_u32 s37, s43, s9
	s_add_i32 s31, s44, 0
	v_lshl_or_b32 v134, v2, 12, v3
	s_add_i32 m0, s31, 0x10000
	v_lshl_or_b32 v130, v5, 12, v3
	global_load_lds_dwordx4 v134, s[36:37]
	s_add_i32 m0, s31, 0x12000
	s_add_u32 s8, s36, 0x80000
	global_load_lds_dwordx4 v130, s[36:37]
	s_addc_u32 s9, s37, 0
	s_add_i32 m0, s31, 0x14000
	v_and_or_b32 v2, v4, 48, v14
	global_load_lds_dwordx4 v134, s[8:9]
	s_add_i32 m0, s31, 0x16000
	s_add_u32 s34, s40, s6
	s_addc_u32 s35, s41, s7
	s_add_i32 s47, s31, 0x2000
	v_lshl_or_b32 v136, v2, 12, v3
	global_load_lds_dwordx4 v130, s[8:9]
	s_mov_b32 m0, s31
	s_add_u32 s6, s34, 0x80000
	global_load_lds_dwordx4 v136, s[34:35]
	s_mov_b32 m0, s47
	s_addc_u32 s7, s35, 0
	s_add_i32 s48, s31, 0x4000
	global_load_lds_dwordx4 v132, s[34:35]
	s_mov_b32 m0, s48
	s_add_i32 s49, s31, 0x6000
	global_load_lds_dwordx4 v136, s[6:7]
	s_mov_b32 m0, s49
	s_load_dwordx2 s[4:5], s[4:5], 0xb8
	global_load_lds_dwordx4 v132, s[6:7]
	v_mov_b32_e32 v135, 0
	v_mov_b32_e32 v131, v135
	v_mov_b32_e32 v137, v135
	v_mov_b32_e32 v133, v135
	s_cmp_eq_u32 s14, 1
	s_mov_b32 s50, 0
	v_lshl_add_u64 v[8:9], s[36:37], 0, v[134:135]
	v_lshl_add_u64 v[6:7], s[36:37], 0, v[130:131]
	v_lshl_add_u64 v[2:3], s[34:35], 0, v[136:137]
	s_cselect_b64 s[6:7], -1, 0
	s_cmp_lg_u32 s14, 1
	v_lshl_add_u64 v[4:5], s[34:35], 0, v[132:133]
	s_cbranch_scc1 .LBB0_800
	s_barrier

.LBB0_867:
	.p2alignl 8, 3212836864
	s_nop 0
	s_nop 0
	s_nop 0
	s_nop 0
	s_nop 0
	s_nop 0
	s_nop 0
	s_nop 0
	s_cmp_lt_i32 s84, 13
	s_cselect_b64 s[4:5], -1, 0
	s_cmp_gt_i32 s85, 12
	s_cselect_b64 s[6:7], -1, 0
	s_and_b64 s[4:5], s[4:5], s[6:7]
	s_andn2_b64 vcc, exec, s[4:5]
	s_cbranch_vccnz .LBB0_974
	s_and_b32 s3, s2, 7
	s_ashr_i32 s14, s33, 6
	s_mul_i32 s56, s14, s3
	s_ashr_i32 s3, s2, 6
	s_add_i32 s56, s56, s3
	s_mov_b64 s[8:9], s[70:71]
	s_mov_b64 s[26:27], s[70:71]
	s_mov_b64 s[4:5], s[70:71]
	s_mov_b64 s[6:7], s[70:71]
	s_mov_b64 s[10:11], s[70:71]
	s_mov_b64 s[12:13], s[70:71]
	s_mov_b64 s[22:23], s[70:71]
	s_mov_b64 s[24:25], s[70:71]
	s_mov_b64 s[28:29], s[70:71]
	s_mov_b64 s[30:31], s[70:71]
	s_mov_b64 s[34:35], s[70:71]
	s_mov_b64 s[38:39], s[70:71]
	s_mov_b64 s[40:41], s[70:71]
	s_mov_b64 s[42:43], s[70:71]
	s_cmp_gt_i32 s56, 63
	v_readfirstlane_b32 s14, v0
	s_cbranch_scc1 .LBB0_920
	s_load_dwordx2 s[8:9], s[8:9], 0xb8
	s_nop 0
	s_load_dwordx2 s[26:27], s[26:27], 0xb8
	v_lshrrev_b32_e32 v2, 5, v0
	v_lshrrev_b32_e32 v4, 1, v0
	v_and_b32_e32 v2, 4, v2
	v_bfe_u32 v3, v0, 2, 2
	v_and_b32_e32 v4, 24, v4
	v_lshlrev_b32_e32 v216, 4, v0
	v_or3_b32 v2, v2, v3, v4
	v_bfe_u32 v3, v0, 3, 25
	v_and_b32_e32 v5, 32, v0
	s_waitcnt lgkmcnt(0)
	s_add_u32 s57, s8, 0x20000000
	v_or_b32_e32 v3, 64, v3
	s_movk_i32 s8, 0x60
	v_bitop3_b32 v10, v216, v5, 48 bitop3:0x6c
	v_and_b32_e32 v11, 64, v0
	v_and_or_b32 v4, v3, s8, v2
	v_or_b32_e32 v5, v10, v11
	v_mul_u32_u24_e32 v4, 0x1600, v4
	v_lshrrev_b32_e32 v5, 1, v5
	v_or_b32_e32 v4, v4, v5
	v_lshlrev_b32_e32 v146, 1, v4
	v_bfe_u32 v4, v0, 2, 4
	s_movk_i32 s8, 0x70
	v_and_or_b32 v3, v3, s8, v4
	s_addc_u32 s60, s9, 0
	s_lshr_b32 s18, s14, 6
	s_bfe_u32 s16, s2, 0x30003
	v_mul_u32_u24_e32 v12, 0x1600, v3
	s_lshr_b32 s17, s14, 8
	s_lshl_b32 s3, s18, 10
	v_or_b32_e32 v3, v12, v5
	s_mul_i32 s15, s16, 0x2c0000
	v_lshlrev_b32_e32 v148, 1, v3
	v_lshrrev_b32_e32 v3, 3, v0
	s_add_u32 s20, s26, s15
	v_and_or_b32 v2, v3, 32, v2
	s_addc_u32 s21, s27, 0
	v_mul_u32_u24_e32 v2, 0x1600, v2
	s_add_u32 s8, s20, 0xea00000
	v_or_b32_e32 v2, v2, v5
	s_addc_u32 s9, s21, 0
	s_add_i32 s61, s3, 0
	v_lshlrev_b32_e32 v150, 1, v2
	s_add_i32 m0, s61, 0x10000
	v_and_or_b32 v2, v3, 48, v4
	global_load_lds_dwordx4 v150, s[8:9]
	s_add_i32 m0, s61, 0x12000
	s_add_u32 s20, s20, 0xeb60000
	global_load_lds_dwordx4 v146, s[8:9]
	s_addc_u32 s21, s21, 0
	s_add_i32 m0, s61, 0x14000
	s_mul_i32 s36, s56, 0x2c0000
	global_load_lds_dwordx4 v150, s[20:21]
	s_add_i32 m0, s61, 0x16000
	v_mul_u32_u24_e32 v13, 0x1600, v2
	s_mul_hi_i32 s19, s56, 0x2c0000
	s_add_u32 s36, s57, s36
	v_or_b32_e32 v2, v5, v13
	s_addc_u32 s37, s60, s19
	s_add_i32 s62, s61, 0x2000
	v_lshlrev_b32_e32 v152, 1, v2
	global_load_lds_dwordx4 v146, s[20:21]
	s_mov_b32 m0, s61
	s_add_u32 s20, s36, 0x160000
	global_load_lds_dwordx4 v152, s[36:37]
	s_mov_b32 m0, s62
	s_addc_u32 s21, s37, 0
	s_add_i32 s63, s61, 0x4000
	global_load_lds_dwordx4 v148, s[36:37]
	s_mov_b32 m0, s63
	s_add_i32 s64, s61, 0x6000
	global_load_lds_dwordx4 v152, s[20:21]
	s_mov_b32 m0, s64
	v_mov_b32_e32 v151, 0
	global_load_lds_dwordx4 v148, s[20:21]
	s_load_dwordx2 s[52:53], s[4:5], 0xb0
	s_load_dwordx2 s[48:49], s[6:7], 0xb0
	s_load_dwordx2 s[54:55], s[10:11], 0xb8
	s_nop 0
	s_load_dwordx2 s[6:7], s[12:13], 0xb8
	s_load_dwordx2 s[4:5], s[22:23], 0xb8
	s_load_dwordx2 s[10:11], s[24:25], 0xb8
	s_load_dwordx2 s[50:51], s[28:29], 0xb8
	s_load_dwordx2 s[46:47], s[30:31], 0xb8
	s_load_dwordx2 s[44:45], s[34:35], 0xb8
	s_nop 0
	s_load_dwordx2 s[34:35], s[38:39], 0xb8
	s_load_dwordx2 s[30:31], s[40:41], 0xb8
	s_load_dwordx2 s[28:29], s[42:43], 0xb8
	v_mov_b32_e32 v147, v151
	v_mov_b32_e32 v153, v151
	v_mov_b32_e32 v149, v151
	s_cmp_eq_u32 s17, 1
	s_mov_b32 s65, 0
	v_lshl_add_u64 v[8:9], s[8:9], 0, v[150:151]
	v_lshl_add_u64 v[6:7], s[8:9], 0, v[146:147]
	v_lshl_add_u64 v[2:3], s[36:37], 0, v[152:153]
	s_cselect_b64 s[12:13], -1, 0
	s_cmp_lg_u32 s17, 1
	v_lshl_add_u64 v[4:5], s[36:37], 0, v[148:149]
	s_cbranch_scc1 .LBB0_871
	s_barrier

.LBB0_974:
	.p2alignl 8, 3212836864
	s_nop 0
	s_nop 0
	s_nop 0
	s_nop 0
	s_nop 0
	s_nop 0
	s_nop 0
	s_nop 0
	s_cmp_lt_i32 s84, 15
	s_cselect_b64 s[4:5], -1, 0
	s_cmp_gt_i32 s85, 14
	s_cselect_b64 s[6:7], -1, 0
	s_and_b64 s[4:5], s[4:5], s[6:7]
	s_andn2_b64 vcc, exec, s[4:5]
	s_cbranch_vccnz .LBB0_1015
	s_cmpk_lt_i32 s2, 0xc0
	s_mov_b64 s[8:9], s[70:71]
	s_mov_b64 s[28:29], s[70:71]
	s_mov_b64 s[4:5], s[70:71]
	s_mov_b64 s[6:7], s[70:71]
	s_mov_b64 s[12:13], s[70:71]
	s_mov_b64 s[22:23], s[70:71]
	s_mov_b64 s[24:25], s[70:71]
	s_mov_b64 s[26:27], s[70:71]
	s_cselect_b64 s[30:31], -1, 0
	s_cmpk_gt_i32 s2, 0xbf
	v_readfirstlane_b32 s3, v0
	s_cbranch_scc1 .LBB0_977
	s_ashr_i32 s10, s2, 31
	s_lshr_b32 s10, s10, 29
	s_add_i32 s10, s2, s10
	s_ashr_i32 s11, s10, 3
	s_and_b32 s10, s10, -8
	s_sub_i32 s10, s2, s10
	s_cmp_lt_i32 s10, 0
	s_cselect_b32 s14, 25, 24
	s_mul_i32 s10, s10, s14
	s_add_i32 s10, s10, s11
	s_mul_hi_i32 s11, s10, 0x2aaaaaab
	s_lshr_b32 s14, s11, 31
	s_ashr_i32 s11, s11, 2
	s_add_i32 s11, s11, s14
	s_lshl_b32 s14, s11, 3
	s_mul_i32 s11, s11, 24
	s_sub_i32 s10, s10, s11
	s_bfe_i32 s11, s10, 0x80000
	s_bfe_u32 s11, s11, 0x3000c
	s_add_i32 s11, s10, s11
	s_bfe_i32 s15, s11, 0x80000
	s_and_b32 s11, s11, 0xf8
	s_sub_i32 s10, s10, s11
	s_sext_i32_i16 s15, s15
	s_sext_i32_i8 s10, s10
	s_add_i32 s50, s14, s10
	s_ashr_i32 s10, s15, 3

.LBB0_1015:
	.p2alignl 8, 3212836864
	s_nop 0
	s_nop 0
	s_nop 0
	s_nop 0
	s_nop 0
	s_nop 0
	s_nop 0
	s_nop 0
	s_nop 0
	s_nop 0
	s_nop 0
	s_nop 0
	s_nop 0
	s_nop 0
	s_cmp_lt_i32 s84, 16
	s_cselect_b64 s[4:5], -1, 0
	s_cmp_gt_i32 s85, 15
	s_cselect_b64 s[6:7], -1, 0
	s_and_b64 s[4:5], s[4:5], s[6:7]
	s_andn2_b64 vcc, exec, s[4:5]
	s_cbranch_vccnz .LBB0_1086
	s_mov_b64 s[6:7], s[70:71]
	s_mov_b64 s[8:9], s[70:71]
	s_mov_b64 s[4:5], s[70:71]
	s_cmpk_gt_i32 s2, 0xaff
	v_readfirstlane_b32 s13, v0
	s_cbranch_scc1 .LBB0_1032
	s_load_dwordx2 s[10:11], s[6:7], 0xb8
	s_load_dwordx2 s[14:15], s[8:9], 0xb8
	v_lshrrev_b32_e32 v2, 5, v0
	v_lshrrev_b32_e32 v4, 1, v0
	v_and_b32_e32 v2, 4, v2
	v_bfe_u32 v3, v0, 2, 2
	v_and_b32_e32 v13, 24, v4
	s_waitcnt lgkmcnt(0)
	s_add_u32 s40, s10, 0x18000000
	v_or3_b32 v2, v2, v3, v13
	v_lshlrev_b32_e32 v3, 4, v0
	s_addc_u32 s41, s11, 0
	v_or_b32_e32 v10, 0x2000, v3
	s_add_u32 s42, s14, 0x7c00000
	v_lshrrev_b32_e32 v4, 7, v10
	s_movk_i32 s6, 0x60
	s_addc_u32 s43, s15, 0
	v_and_or_b32 v5, v4, s6, v2
	v_bfe_u32 v14, v0, 2, 4
	s_movk_i32 s6, 0x70
	s_ashr_i32 s45, s2, 31
	v_and_or_b32 v4, v4, s6, v14
	s_lshr_b32 s6, s45, 29
	s_add_i32 s6, s2, s6
	s_lshr_b32 s3, s13, 6
	s_ashr_i32 s7, s6, 3
	s_and_b32 s6, s6, -8
	s_lshr_b32 s14, s13, 8
	s_lshl_b32 s44, s3, 10
	s_sub_i32 s6, s2, s6
	s_cmp_lt_i32 s6, 0
	s_movk_i32 s46, 0x161
	s_cselect_b32 s8, s46, 0x160
	s_mul_i32 s6, s6, s8
	s_add_i32 s6, s6, s7
	s_mul_hi_i32 s7, s6, 0x2e8ba2e9
	s_lshr_b32 s8, s7, 31
	s_ashr_i32 s7, s7, 6
	s_add_i32 s7, s7, s8
	s_lshl_b32 s8, s7, 3
	s_mulk_i32 s7, 0x160
	s_sub_i32 s6, s6, s7
	s_sext_i32_i16 s7, s6
	s_bfe_u32 s7, s7, 0x3001c
	s_add_i32 s7, s6, s7
	s_sext_i32_i16 s9, s7
	s_and_b32 s7, s7, 0xfff8
	s_sub_i32 s6, s6, s7
	s_sext_i32_i16 s6, s6
	v_and_b32_e32 v6, 32, v0
	s_lshr_b32 s12, s9, 3
	s_add_i32 s30, s8, s6
	v_bitop3_b32 v11, v3, v6, 48 bitop3:0x6c
	v_and_b32_e32 v12, 64, v0
	s_ashr_i32 s31, s30, 31
	s_bfe_i64 s[8:9], s[12:13], 0x100000
	v_or_b32_e32 v3, v11, v12
	s_lshl_b64 s[6:7], s[30:31], 20
	s_lshl_b64 s[8:9], s[8:9], 20
	v_lshl_or_b32 v132, v4, 12, v3
	v_lshrrev_b32_e32 v4, 3, v0
	s_add_u32 s36, s42, s8
	v_and_or_b32 v2, v4, 32, v2
	s_addc_u32 s37, s43, s9
	s_add_i32 s31, s44, 0
	v_lshl_or_b32 v134, v2, 12, v3
	s_add_i32 m0, s31, 0x10000
	v_lshl_or_b32 v130, v5, 12, v3
	global_load_lds_dwordx4 v134, s[36:37]
	s_add_i32 m0, s31, 0x12000
	s_add_u32 s8, s36, 0x80000
	global_load_lds_dwordx4 v130, s[36:37]
	s_addc_u32 s9, s37, 0
	s_add_i32 m0, s31, 0x14000
	v_and_or_b32 v2, v4, 48, v14
	global_load_lds_dwordx4 v134, s[8:9]
	s_add_i32 m0, s31, 0x16000
	s_add_u32 s34, s40, s6
	s_addc_u32 s35, s41, s7
	s_add_i32 s47, s31, 0x2000
	v_lshl_or_b32 v136, v2, 12, v3
	global_load_lds_dwordx4 v130, s[8:9]
	s_mov_b32 m0, s31
	s_add_u32 s6, s34, 0x80000
	global_load_lds_dwordx4 v136, s[34:35]
	s_mov_b32 m0, s47
	s_addc_u32 s7, s35, 0
	s_add_i32 s48, s31, 0x4000
	global_load_lds_dwordx4 v132, s[34:35]
	s_mov_b32 m0, s48
	s_add_i32 s49, s31, 0x6000
	global_load_lds_dwordx4 v136, s[6:7]
	s_mov_b32 m0, s49
	s_load_dwordx2 s[4:5], s[4:5], 0xb8
	global_load_lds_dwordx4 v132, s[6:7]
	v_mov_b32_e32 v135, 0
	v_mov_b32_e32 v131, v135
	v_mov_b32_e32 v137, v135
	v_mov_b32_e32 v133, v135
	s_cmp_eq_u32 s14, 1
	s_mov_b32 s50, 0
	v_lshl_add_u64 v[8:9], s[36:37], 0, v[134:135]
	v_lshl_add_u64 v[6:7], s[36:37], 0, v[130:131]
	v_lshl_add_u64 v[2:3], s[34:35], 0, v[136:137]
	s_cselect_b64 s[6:7], -1, 0
	s_cmp_lg_u32 s14, 1
	v_lshl_add_u64 v[4:5], s[34:35], 0, v[132:133]
	s_cbranch_scc1 .LBB0_1019
	s_barrier

.LBB0_1086:
	.p2alignl 8, 3212836864
	s_nop 0
	s_nop 0
	s_nop 0
	s_nop 0
	s_nop 0
	s_nop 0
	s_nop 0
	s_nop 0
	s_cmp_lt_i32 s84, 17
	s_cselect_b64 s[4:5], -1, 0
	s_cmp_gt_i32 s85, 16
	s_cselect_b64 s[6:7], -1, 0
	s_and_b64 s[4:5], s[4:5], s[6:7]
	s_andn2_b64 vcc, exec, s[4:5]
	s_cbranch_vccnz .LBB0_1193
	s_and_b32 s3, s2, 7
	s_ashr_i32 s14, s33, 6
	s_mul_i32 s48, s14, s3
	s_ashr_i32 s3, s2, 6
	s_add_i32 s48, s48, s3
	s_mov_b64 s[8:9], s[70:71]
	s_mov_b64 s[34:35], s[70:71]
	s_mov_b64 s[4:5], s[70:71]
	s_mov_b64 s[6:7], s[70:71]
	s_mov_b64 s[10:11], s[70:71]
	s_mov_b64 s[12:13], s[70:71]
	s_mov_b64 s[22:23], s[70:71]
	s_mov_b64 s[24:25], s[70:71]
	s_mov_b64 s[26:27], s[70:71]
	s_mov_b64 s[28:29], s[70:71]
	s_mov_b64 s[30:31], s[70:71]
	s_cmp_gt_i32 s48, 63
	v_readfirstlane_b32 s14, v0
	s_cbranch_scc1 .LBB0_1139
	v_lshrrev_b32_e32 v2, 5, v0
	v_lshrrev_b32_e32 v4, 1, v0
	v_and_b32_e32 v2, 4, v2
	v_bfe_u32 v3, v0, 2, 2
	v_and_b32_e32 v4, 24, v4
	v_lshlrev_b32_e32 v210, 4, v0
	v_or3_b32 v2, v2, v3, v4
	v_bfe_u32 v3, v0, 3, 25
	s_waitcnt lgkmcnt(0)
	v_and_b32_e32 v5, 32, v0
	s_load_dwordx2 s[16:17], s[8:9], 0xb8
	s_load_dwordx2 s[18:19], s[34:35], 0xb8
	v_or_b32_e32 v3, 64, v3
	s_movk_i32 s8, 0x60
	v_bitop3_b32 v10, v210, v5, 48 bitop3:0x6c
	v_and_b32_e32 v11, 64, v0
	v_and_or_b32 v4, v3, s8, v2
	v_or_b32_e32 v5, v10, v11
	v_mul_u32_u24_e32 v4, 0x1600, v4
	v_lshrrev_b32_e32 v5, 1, v5
	v_or_b32_e32 v4, v4, v5
	v_lshlrev_b32_e32 v146, 1, v4
	v_bfe_u32 v4, v0, 2, 4
	s_movk_i32 s8, 0x70
	s_waitcnt lgkmcnt(0)
	s_add_u32 s49, s16, 0x20000000
	v_and_or_b32 v3, v3, s8, v4
	s_addc_u32 s50, s17, 0
	s_lshr_b32 s17, s14, 6
	s_bfe_u32 s15, s2, 0x30003
	v_mul_u32_u24_e32 v12, 0x1600, v3
	s_lshr_b32 s16, s14, 8
	s_lshl_b32 s3, s17, 10
	v_or_b32_e32 v3, v12, v5
	s_mul_i32 s8, s15, 0x2c0000
	v_lshlrev_b32_e32 v148, 1, v3
	v_lshrrev_b32_e32 v3, 3, v0
	s_add_u32 s18, s18, s8
	v_and_or_b32 v2, v3, 32, v2
	s_addc_u32 s19, s19, 0
	v_mul_u32_u24_e32 v2, 0x1600, v2
	s_add_u32 s8, s18, 0x10000000
	v_or_b32_e32 v2, v2, v5
	s_addc_u32 s9, s19, 0
	s_add_i32 s51, s3, 0
	v_lshlrev_b32_e32 v150, 1, v2
	s_add_i32 m0, s51, 0x10000
	v_and_or_b32 v2, v3, 48, v4
	global_load_lds_dwordx4 v150, s[8:9]
	s_add_i32 m0, s51, 0x12000
	s_add_u32 s18, s18, 0x10160000
	global_load_lds_dwordx4 v146, s[8:9]
	s_addc_u32 s19, s19, 0
	s_add_i32 m0, s51, 0x14000
	s_mul_i32 s21, s48, 0x2c0000
	global_load_lds_dwordx4 v150, s[18:19]
	s_add_i32 m0, s51, 0x16000
	v_mul_u32_u24_e32 v13, 0x1600, v2
	s_mul_hi_i32 s20, s48, 0x2c0000
	s_add_u32 s34, s49, s21
	v_or_b32_e32 v2, v5, v13
	s_addc_u32 s35, s50, s20
	s_add_i32 s52, s51, 0x2000
	v_lshlrev_b32_e32 v152, 1, v2
	global_load_lds_dwordx4 v146, s[18:19]
	s_mov_b32 m0, s51
	s_add_u32 s18, s34, 0x160000
	global_load_lds_dwordx4 v152, s[34:35]
	s_mov_b32 m0, s52
	s_addc_u32 s19, s35, 0
	s_add_i32 s53, s51, 0x4000
	global_load_lds_dwordx4 v148, s[34:35]
	s_mov_b32 m0, s53
	s_add_i32 s54, s51, 0x6000
	global_load_lds_dwordx4 v152, s[18:19]
	s_mov_b32 m0, s54
	v_mov_b32_e32 v151, 0
	global_load_lds_dwordx4 v148, s[18:19]
	s_load_dwordx2 s[40:41], s[4:5], 0xb0
	s_load_dwordx2 s[36:37], s[6:7], 0xb0
	s_load_dwordx2 s[42:43], s[10:11], 0xb8
	s_nop 0
	s_load_dwordx2 s[6:7], s[12:13], 0xb8
	s_load_dwordx2 s[4:5], s[22:23], 0xb8
	s_load_dwordx2 s[10:11], s[24:25], 0xb8
	s_load_dwordx2 s[38:39], s[26:27], 0xb8
	s_nop 0
	s_load_dwordx2 s[28:29], s[28:29], 0xb8
	s_nop 0
	s_load_dwordx2 s[26:27], s[30:31], 0xb8
	v_mov_b32_e32 v147, v151
	v_mov_b32_e32 v153, v151
	v_mov_b32_e32 v149, v151
	s_cmp_eq_u32 s16, 1
	s_mov_b32 s55, 0
	v_lshl_add_u64 v[8:9], s[8:9], 0, v[150:151]
	v_lshl_add_u64 v[6:7], s[8:9], 0, v[146:147]
	v_lshl_add_u64 v[2:3], s[34:35], 0, v[152:153]
	s_cselect_b64 s[12:13], -1, 0
	s_cmp_lg_u32 s16, 1
	v_lshl_add_u64 v[4:5], s[34:35], 0, v[148:149]
	s_cbranch_scc1 .LBB0_1090
	s_barrier

.LBB0_1193:
	.p2alignl 8, 3212836864
	s_nop 0
	s_nop 0
	s_nop 0
	s_nop 0
	s_nop 0
	s_nop 0
	s_nop 0
	s_nop 0
	s_cmp_lt_i32 s84, 19
	s_cselect_b64 s[4:5], -1, 0
	s_cmp_gt_i32 s85, 18
	s_cselect_b64 s[6:7], -1, 0
	s_and_b64 s[4:5], s[4:5], s[6:7]
	s_andn2_b64 vcc, exec, s[4:5]
	s_cbranch_vccnz .LBB0_1326
	s_mov_b64 s[4:5], s[70:71]
	s_load_dwordx2 s[12:13], s[4:5], 0xb8
	s_mov_b64 s[4:5], s[70:71]
	s_load_dwordx2 s[22:23], s[4:5], 0xb8
	s_mov_b64 s[4:5], s[70:71]
	s_mov_b64 s[6:7], s[70:71]
	s_load_dwordx2 s[4:5], s[4:5], 0xb8
	s_load_dwordx2 s[8:9], s[6:7], 0x90
	s_mov_b64 s[6:7], s[70:71]
	s_load_dwordx2 s[6:7], s[6:7], 0xb8
	s_cmpk_lt_i32 s2, 0x80
	s_cselect_b64 s[24:25], -1, 0
	s_cmpk_gt_i32 s2, 0x7f
	v_readfirstlane_b32 s3, v0
	s_cbranch_scc1 .LBB0_1200
	s_ashr_i32 s10, s2, 31
	s_lshr_b32 s10, s10, 29
	s_add_i32 s14, s2, s10
	s_and_b32 s10, s14, -8
	s_sub_i32 s15, s2, s10
	s_cmp_gt_i32 s15, -1
	s_cbranch_scc0 .LBB0_1197
	s_lshl_b32 s16, s15, 4
	s_cbranch_execz .LBB0_1198
	s_branch .LBB0_1199

.LBB0_1326:
	.p2alignl 8, 3212836864
	s_nop 0
	s_nop 0
	s_nop 0
	s_nop 0
	s_nop 0
	s_nop 0
	s_nop 0
	s_nop 0
	s_cmp_lt_i32 s84, 20
	s_cselect_b64 s[4:5], -1, 0
	s_cmp_gt_i32 s85, 19
	s_cselect_b64 s[6:7], -1, 0
	s_and_b64 s[4:5], s[4:5], s[6:7]
	s_andn2_b64 vcc, exec, s[4:5]
	s_cbranch_vccnz .LBB0_1401
	s_mov_b64 s[6:7], s[70:71]
	s_mov_b64 s[22:23], s[70:71]
	s_mov_b64 s[4:5], s[70:71]
	s_mov_b64 s[8:9], s[70:71]
	s_mov_b64 s[10:11], s[70:71]
	s_mov_b64 s[12:13], s[70:71]
	s_cmpk_gt_i32 s2, 0x2ff
	v_readfirstlane_b32 s3, v0
	s_cbranch_scc1 .LBB0_1347
	s_load_dwordx2 s[14:15], s[6:7], 0xb8
	s_load_dwordx2 s[16:17], s[22:23], 0xb8
	v_lshrrev_b32_e32 v2, 5, v0
	v_and_b32_e32 v3, 4, v2
	v_lshrrev_b32_e32 v2, 1, v0
	s_waitcnt lgkmcnt(0)
	s_add_u32 s42, s14, 0x2c000000
	v_bfe_u32 v4, v0, 2, 2
	v_and_b32_e32 v2, 24, v2
	v_lshlrev_b32_e32 v5, 4, v0
	s_addc_u32 s43, s15, 0
	v_or3_b32 v4, v3, v4, v2
	v_or_b32_e32 v3, 0x2000, v5
	s_add_u32 s44, s16, 0x17500000
	v_lshrrev_b32_e32 v6, 7, v3
	s_movk_i32 s6, 0x60
	s_addc_u32 s45, s17, 0
	v_and_or_b32 v7, v6, s6, v4
	v_bfe_u32 v14, v0, 2, 4
	s_movk_i32 s6, 0x70
	s_ashr_i32 s47, s2, 31
	v_and_or_b32 v6, v6, s6, v14
	s_lshr_b32 s6, s47, 29
	s_add_i32 s6, s2, s6
	s_lshr_b32 s15, s3, 6
	s_ashr_i32 s7, s6, 3
	s_and_b32 s6, s6, -8
	s_lshr_b32 s14, s3, 8
	s_lshl_b32 s46, s15, 10
	s_sub_i32 s6, s2, s6
	s_cmp_lt_i32 s6, 0
	s_movk_i32 s48, 0x61
	s_cselect_b32 s16, s48, 0x60
	s_mul_i32 s6, s6, s16
	s_add_i32 s6, s6, s7
	s_mul_hi_i32 s7, s6, 0x2aaaaaab
	s_lshr_b32 s16, s7, 31
	s_ashr_i32 s7, s7, 4
	s_add_i32 s7, s7, s16
	s_lshl_b32 s16, s7, 3
	s_mulk_i32 s7, 0x60
	s_sub_i32 s6, s6, s7
	s_bfe_i32 s7, s6, 0x80000
	s_bfe_u32 s7, s7, 0x3000c
	s_add_i32 s7, s6, s7
	s_bfe_i32 s17, s7, 0x80000
	s_and_b32 s7, s7, 0xf8
	s_sub_i32 s6, s6, s7
	s_sext_i32_i16 s17, s17
	s_sext_i32_i8 s6, s6
	v_and_b32_e32 v8, 32, v0
	s_lshr_b32 s24, s17, 3
	s_add_i32 s6, s16, s6
	v_bitop3_b32 v12, v5, v8, 48 bitop3:0x6c
	v_and_b32_e32 v13, 64, v0
	s_ashr_i32 s7, s6, 31
	s_bfe_i64 s[18:19], s[24:25], 0x100000
	v_or_b32_e32 v5, v12, v13
	s_lshl_b64 s[16:17], s[6:7], 18
	s_lshl_b64 s[18:19], s[18:19], 18
	v_lshl_or_b32 v132, v6, 10, v5
	v_lshrrev_b32_e32 v6, 3, v0
	s_add_u32 s38, s44, s18
	v_and_or_b32 v4, v6, 32, v4
	s_addc_u32 s39, s45, s19
	s_add_i32 s49, s46, 0
	v_lshl_or_b32 v134, v4, 10, v5
	s_add_i32 m0, s49, 0x10000
	v_lshl_or_b32 v130, v7, 10, v5
	global_load_lds_dwordx4 v134, s[38:39]
	s_add_i32 m0, s49, 0x12000
	s_add_u32 s18, s38, 0x20000
	global_load_lds_dwordx4 v130, s[38:39]
	s_addc_u32 s19, s39, 0
	s_add_i32 m0, s49, 0x14000
	v_and_or_b32 v4, v6, 48, v14
	global_load_lds_dwordx4 v134, s[18:19]
	s_add_i32 m0, s49, 0x16000
	s_add_u32 s36, s42, s16
	s_addc_u32 s37, s43, s17
	s_add_i32 s50, s49, 0x2000
	v_lshl_or_b32 v136, v4, 10, v5
	global_load_lds_dwordx4 v130, s[18:19]
	s_mov_b32 m0, s49
	s_add_u32 s16, s36, 0x20000
	global_load_lds_dwordx4 v136, s[36:37]
	s_mov_b32 m0, s50
	s_addc_u32 s17, s37, 0
	s_add_i32 s51, s49, 0x4000
	global_load_lds_dwordx4 v132, s[36:37]
	s_mov_b32 m0, s51
	s_add_i32 s52, s49, 0x6000
	global_load_lds_dwordx4 v136, s[16:17]
	s_mov_b32 m0, s52
	v_mov_b32_e32 v139, 0
	global_load_lds_dwordx4 v132, s[16:17]
	s_load_dwordx2 s[28:29], s[4:5], 0xb8
	s_load_dwordx2 s[22:23], s[8:9], 0xb8
	s_load_dwordx2 s[26:27], s[10:11], 0xb8
	s_nop 0
	s_load_dwordx2 s[4:5], s[12:13], 0xb8
	v_mov_b32_e32 v135, v139
	v_mov_b32_e32 v131, v139
	v_mov_b32_e32 v137, v139
	v_mov_b32_e32 v133, v139
	s_cmp_eq_u32 s14, 1
	s_mov_b32 s7, 0
	v_lshl_add_u64 v[10:11], s[38:39], 0, v[134:135]
	v_lshl_add_u64 v[8:9], s[38:39], 0, v[130:131]
	v_lshl_add_u64 v[4:5], s[36:37], 0, v[136:137]
	s_cselect_b64 s[8:9], -1, 0
	s_cmp_lg_u32 s14, 1
	v_lshl_add_u64 v[6:7], s[36:37], 0, v[132:133]
	s_cbranch_scc1 .LBB0_1330
	s_barrier

.LBB0_1401:
	.p2alignl 8, 3212836864
	s_nop 0
	s_nop 0
	s_nop 0
	s_nop 0
	s_nop 0
	s_nop 0
	s_nop 0
	s_nop 0
	s_cmp_lt_i32 s84, 21
	s_cselect_b64 s[4:5], -1, 0
	s_cmp_gt_i32 s85, 20
	s_cselect_b64 s[6:7], -1, 0
	s_and_b64 s[4:5], s[4:5], s[6:7]
	s_andn2_b64 vcc, exec, s[4:5]
	s_cbranch_vccnz .LBB0_1489
	s_mov_b64 s[6:7], s[70:71]
	v_writelane_b32 v254, s94, 0
	s_mov_b64 s[8:9], s[70:71]
	s_mov_b64 s[10:11], s[70:71]
	v_writelane_b32 v254, s95, 1
	v_writelane_b32 v254, s92, 2
	s_mov_b64 s[22:23], s[70:71]
	s_cmpk_gt_i32 s72, 0x1ff
	v_writelane_b32 v254, s93, 3
	v_writelane_b32 v254, s90, 4
	v_writelane_b32 v254, s88, 5
	s_nop 1
	v_writelane_b32 v254, s89, 6
	v_writelane_b32 v254, s86, 7
	s_nop 1
	v_writelane_b32 v254, s87, 8
	v_writelane_b32 v254, s85, 9
	v_writelane_b32 v254, s84, 10
	v_writelane_b32 v254, s2, 11
	v_writelane_b32 v254, s70, 12
	s_nop 1
	v_writelane_b32 v254, s71, 13
	s_cbranch_scc1 .LBB0_1435
	v_lshrrev_b32_e32 v3, 5, v1
	v_lshlrev_b32_e32 v6, 5, v1
	v_lshlrev_b32_e32 v8, 3, v0
	v_and_b32_e32 v6, 0x180, v6
	v_lshlrev_b32_e32 v7, 9, v3
	v_and_b32_e32 v8, 8, v8
	v_or3_b32 v6, v7, v6, v8
	v_lshrrev_b32_e32 v7, 3, v0
	v_lshrrev_b32_e32 v2, 1, v1
	v_and_b32_e32 v7, 2, v7
	v_and_or_b32 v7, v2, 1, v7
	s_load_dwordx2 s[14:15], s[8:9], 0xb8
	s_load_dwordx2 s[16:17], s[6:7], 0xb8
	s_load_dwordx2 s[18:19], s[10:11], 0xb8
	s_load_dwordx2 s[12:13], s[22:23], 0xb8
	v_and_or_b32 v8, v2, 4, v7
	v_bitop3_b32 v2, v7, v2, 4 bitop3:0x72
	v_lshl_or_b32 v163, v8, 4, v6
	v_lshl_or_b32 v212, v2, 4, v6
	v_lshrrev_b32_e32 v2, 4, v1
	v_and_b32_e32 v6, 7, v0
	s_waitcnt lgkmcnt(0)
	s_add_u32 s35, s14, 0x2d400000
	v_bitop3_b32 v7, v2, v6, 4 bitop3:0x36
	v_lshrrev_b32_e32 v8, 3, v1
	v_bitop3_b32 v2, v2, v0, 7 bitop3:0x78
	s_addc_u32 s0, s15, 0
	v_lshrrev_b32_e32 v4, 2, v1
	v_lshlrev_b32_e32 v7, 3, v7
	v_lshlrev_b32_e32 v9, 6, v8
	v_lshlrev_b32_e32 v8, 11, v8
	v_lshlrev_b32_e32 v2, 3, v2
	v_writelane_b32 v254, s0, 14
	s_add_u32 s0, s18, 0x2d000000
	v_or_b32_e32 v10, v7, v9
	v_or_b32_e32 v13, v2, v9
	v_or_b32_e32 v14, v2, v8
	v_and_b32_e32 v9, 31, v0
	v_bitop3_b32 v2, v4, v6, 4 bitop3:0x6c
	v_writelane_b32 v254, s0, 15
	s_addc_u32 s0, s19, 0
	v_and_b32_e32 v12, 4, v4
	v_or_b32_e32 v11, v7, v8
	v_lshl_or_b32 v4, v2, 3, v8
	v_mul_u32_u24_e32 v2, 0xc00, v9
	v_lshlrev_b32_e32 v8, 3, v3
	v_writelane_b32 v254, s0, 16
	s_add_u32 s0, s12, 0x31400000
	v_or_b32_e32 v6, v8, v2
	v_mov_b32_e32 v2, 0
	v_writelane_b32 v254, s0, 17
	s_addc_u32 s0, s13, 0
	v_lshlrev_b32_e32 v5, 7, v0
	s_lshl_b32 s6, s59, 11
	v_lshlrev_b32_e32 v6, 1, v6
	v_mov_b32_e32 v7, v2
	v_and_b32_e32 v213, 0xf80, v5
	s_load_dwordx2 s[4:5], s[70:71], 0xb8
	v_bfe_u32 v5, v1, 1, 2
	s_add_i32 s80, s6, 0
	v_lshl_add_u64 v[6:7], s[16:17], 0, v[6:7]
	s_mov_b64 s[6:7], 0x20000000
	v_lshl_add_u64 v[164:165], v[6:7], 0, s[6:7]
	v_bitop3_b32 v6, v5, v3, v12 bitop3:0x36
	v_lshlrev_b32_e32 v214, 4, v6
	v_or_b32_e32 v6, 2, v3
	v_bitop3_b32 v6, v5, v6, v12 bitop3:0x36
	s_lshl_b32 s22, s59, 3
	s_mov_b32 s23, 0
	v_lshlrev_b32_e32 v215, 4, v6
	v_lshl_or_b32 v6, v9, 12, v8
	v_mov_b32_e32 v7, v2
	v_writelane_b32 v254, s0, 18
	s_lshr_b32 s79, s58, 7
	s_mul_i32 s3, s59, 3
	s_lshl_b64 s[24:25], s[22:23], 12
	s_add_i32 s81, s80, 0x12000
	s_lshl_b32 s0, s59, 5
	s_and_b32 s6, s58, 0xffffff00
	s_waitcnt lgkmcnt(0)
	v_lshl_add_u64 v[6:7], s[4:5], 0, v[6:7]
	s_mov_b64 s[4:5], 0x26000000
	s_cmpk_eq_i32 s6, 0x100
	v_lshl_add_u64 v[166:167], v[6:7], 0, s[4:5]
	s_mul_hi_u32 s4, s3, 0x15555556
	s_cselect_b64 s[26:27], -1, 0
	s_cmpk_lt_u32 s58, 0x100
	s_mul_i32 s4, s4, 12
	s_cselect_b64 s[28:29], -1, 0
	s_sub_i32 s18, s3, s4
	s_and_b32 s4, s3, 3
	s_lshr_b32 s5, s58, 3
	s_and_b32 s5, s5, 0x1fffffe0
	s_lshl_b32 s6, s4, 3
	s_or_b32 s22, s5, s6
	v_writelane_b32 v254, s0, 19
	s_lshl_b64 s[0:1], s[22:23], 7
	v_writelane_b32 v254, s0, 20
	s_lshl_b32 s5, s18, 4
	s_and_b32 s19, s5, 0xc0
	v_writelane_b32 v254, s1, 21
	s_lshl_b64 s[0:1], s[22:23], 12
	s_cmp_lt_u32 s4, 2
	s_cselect_b64 vcc, -1, 0
	s_add_i32 s6, s3, 1
	s_mul_hi_u32 s4, s6, 0x15555556
	s_mul_i32 s5, s4, 12
	s_and_b32 s8, s6, 3
	s_sub_i32 s7, s6, s5
	s_lshl_b32 s4, s4, 5
	s_lshl_b32 s5, s8, 3
	s_or_b32 s14, s4, s5
	s_cmp_lt_u32 s7, 8
	s_mov_b32 s15, s23
	s_cselect_b64 s[4:5], -1, 0
	s_lshl_b32 s7, s7, 4
	s_lshl_b64 s[36:37], s[14:15], 7
	s_lshl_b64 s[38:39], s[14:15], 12
	s_and_b32 s15, s7, 0xc0
	s_cmp_lt_u32 s8, 2
	s_cselect_b64 s[8:9], -1, 0
	s_add_i32 s3, s3, 2
	s_lshl_b32 s83, s6, 10
	s_mul_hi_u32 s6, s3, 0x15555556
	s_mul_i32 s7, s6, 12
	s_sub_i32 s20, s3, s7
	s_and_b32 s7, s3, 3
	s_lshl_b32 s6, s6, 5
	s_lshl_b32 s10, s7, 3
	s_or_b32 s16, s6, s10
	s_mov_b32 s17, s23
	s_lshl_b32 s6, s20, 4
	s_lshl_b64 s[40:41], s[16:17], 7
	s_lshl_b64 s[42:43], s[16:17], 12
	s_and_b32 s17, s6, 0xc0
	s_cmp_lt_u32 s7, 2
	s_cselect_b64 s[10:11], -1, 0
	s_add_i32 s6, s22, 64
	s_mov_b32 s7, s23
	s_lshl_b64 s[44:45], s[6:7], 7
	s_lshl_b64 s[46:47], s[6:7], 12
	s_add_i32 s6, s14, 64
	s_lshl_b64 s[48:49], s[6:7], 7
	s_lshl_b64 s[50:51], s[6:7], 12
	s_add_i32 s6, s16, 64
	s_lshl_b32 s84, s3, 10
	s_lshl_b64 s[52:53], s[6:7], 7
	s_lshl_b64 s[54:55], s[6:7], 12
	s_cmp_lt_u32 s18, 8
	s_cselect_b64 s[6:7], -1, 0
	v_cndmask_b32_e64 v8, v11, v14, s[8:9]
	v_cndmask_b32_e64 v9, v10, v13, s[8:9]
	s_and_b64 s[8:9], s[6:7], exec
	s_cselect_b32 s86, 12, 7
	s_and_b64 s[8:9], s[4:5], exec
	s_cselect_b32 s87, 12, 7
	s_cmp_lt_u32 s20, 8
	s_cselect_b64 s[8:9], -1, 0
	v_cndmask_b32_e32 v6, v11, v14, vcc
	v_cndmask_b32_e32 v7, v10, v13, vcc
	v_cndmask_b32_e64 v11, v11, v14, s[10:11]
	v_cndmask_b32_e64 v10, v10, v13, s[10:11]
	s_and_b64 s[10:11], s[8:9], exec
	s_cselect_b32 s88, 12, 7
	s_add_u32 s10, s12, s24
	s_addc_u32 s11, s13, s25
	s_add_u32 s89, s16, 0x80
	v_or_b32_e32 v13, 4, v3
	s_addc_u32 s90, 0, 0
	v_bitop3_b32 v13, v5, v13, v12 bitop3:0x36
	v_or_b32_e32 v3, 6, v3
	s_add_u32 s91, s14, 0x80
	v_lshlrev_b32_e32 v216, 4, v13
	v_bitop3_b32 v3, v5, v3, v12 bitop3:0x36
	v_lshlrev_b32_e32 v12, 1, v4
	v_mov_b32_e32 v13, v2
	s_addc_u32 s92, 0, 0
	v_cndmask_b32_e64 v6, v7, v6, s[6:7]
	v_mov_b32_e32 v7, v2
	v_cndmask_b32_e64 v8, v9, v8, s[4:5]
	v_mov_b32_e32 v9, v2
	v_cndmask_b32_e64 v10, v10, v11, s[8:9]
	v_mov_b32_e32 v11, v2
	v_lshlrev_b32_e32 v217, 4, v3
	v_lshl_add_u64 v[12:13], s[10:11], 0, v[12:13]
	s_mov_b64 s[10:11], 0x31480000
	s_add_u32 s93, s22, 0x80
	v_mbcnt_lo_u32_b32 v3, -1, 0
	v_writelane_b32 v254, s0, 22
	s_mul_i32 s85, s59, 0xc00
	v_lshl_add_u64 v[168:169], v[12:13], 0, s[10:11]
	s_mov_b64 s[56:57], 0x80
	s_addc_u32 s94, 0, 0
	v_lshlrev_b32_e32 v170, 1, v4
	v_mov_b32_e32 v171, v2
	s_mov_b64 s[58:59], 0x40000
	s_lshl_b32 s95, s19, 1
	s_lshl_b32 s96, s15, 1
	s_lshl_b32 s97, s17, 1
	v_lshlrev_b64 v[172:173], 1, v[6:7]
	v_lshlrev_b64 v[174:175], 1, v[8:9]
	v_lshlrev_b64 v[176:177], 1, v[10:11]
	v_mbcnt_hi_u32_b32 v218, -1, v3
	v_mov_b32_e32 v219, 0x1800
	v_writelane_b32 v254, s1, 23
	s_branch .LBB0_1405

.LBB0_1489:
	.p2alignl 8, 3212836864
	s_nop 0
	s_nop 0
	s_nop 0
	s_nop 0
	s_nop 0
	s_nop 0
	s_nop 0
	s_nop 0
	s_cmp_lt_i32 s84, 22
	s_cselect_b64 s[4:5], -1, 0
	s_cmp_gt_i32 s85, 21
	s_cselect_b64 s[6:7], -1, 0
	s_and_b64 s[4:5], s[4:5], s[6:7]
	s_andn2_b64 vcc, exec, s[4:5]
	s_cbranch_vccnz .LBB0_1594
	s_and_b32 s0, s2, 7
	s_ashr_i32 s1, s33, 6
	s_mul_i32 s0, s1, s0
	s_ashr_i32 s1, s2, 6
	s_add_i32 s8, s0, s1
	s_mov_b64 s[10:11], s[70:71]
	s_mov_b64 s[12:13], s[70:71]
	s_mov_b64 s[4:5], s[70:71]
	s_mov_b64 s[6:7], s[70:71]
	s_mov_b64 s[22:23], s[70:71]
	s_mov_b64 s[24:25], s[70:71]
	s_mov_b64 s[26:27], s[70:71]
	s_mov_b64 s[28:29], s[70:71]
	s_mov_b64 s[30:31], s[70:71]
	s_mov_b64 s[34:35], s[70:71]
	s_mov_b64 s[36:37], s[70:71]
	s_cmp_gt_i32 s8, 63
	v_readfirstlane_b32 s3, v0
	s_cbranch_scc1 .LBB0_1540
	s_load_dwordx2 s[14:15], s[10:11], 0xb8
	s_load_dwordx2 s[18:19], s[12:13], 0xb8
	v_lshlrev_b32_e32 v210, 4, v0
	v_lshrrev_b32_e32 v2, 5, v0
	v_lshrrev_b32_e32 v4, 1, v0
	v_and_b32_e32 v2, 4, v2
	v_bfe_u32 v3, v0, 2, 2
	v_and_b32_e32 v4, 24, v4
	v_or_b32_e32 v10, 0x2000, v210
	s_waitcnt lgkmcnt(0)
	s_add_u32 s52, s14, 0x26000000
	v_or3_b32 v2, v2, v3, v4
	v_lshrrev_b32_e32 v3, 7, v10
	s_movk_i32 s0, 0x60
	s_addc_u32 s53, s15, 0
	s_lshr_b32 s16, s3, 6
	s_bfe_u32 s14, s2, 0x30003
	v_and_or_b32 v4, v3, s0, v2
	v_bfe_u32 v13, v0, 2, 4
	s_movk_i32 s0, 0x70
	s_ashr_i32 s9, s8, 31
	s_lshr_b32 s15, s3, 8
	s_lshl_b32 s54, s16, 10
	v_and_b32_e32 v5, 32, v0
	v_and_or_b32 v3, v3, s0, v13
	s_lshl_b64 s[12:13], s[8:9], 20
	s_lshl_b32 s0, s14, 20
	v_bitop3_b32 v11, v210, v5, 48 bitop3:0x6c
	v_and_b32_e32 v12, 64, v0
	s_add_u32 s0, s18, s0
	v_or_b32_e32 v5, v11, v12
	s_addc_u32 s1, s19, 0
	v_lshl_or_b32 v148, v3, 12, v5
	v_lshrrev_b32_e32 v3, 3, v0
	s_add_u32 s10, s0, 0x17800000
	v_and_or_b32 v2, v3, 32, v2
	s_addc_u32 s11, s1, 0
	s_add_i32 s9, s54, 0
	v_lshl_or_b32 v150, v2, 12, v5
	s_add_i32 m0, s9, 0x10000
	v_lshl_or_b32 v146, v4, 12, v5
	global_load_lds_dwordx4 v150, s[10:11]
	s_add_i32 m0, s9, 0x12000
	s_add_u32 s18, s0, 0x17880000
	global_load_lds_dwordx4 v146, s[10:11]
	s_addc_u32 s19, s1, 0
	s_add_i32 m0, s9, 0x14000
	v_and_or_b32 v2, v3, 48, v13
	global_load_lds_dwordx4 v150, s[18:19]
	s_add_i32 m0, s9, 0x16000
	s_add_u32 s12, s52, s12
	s_addc_u32 s13, s53, s13
	s_add_i32 s55, s9, 0x2000
	v_lshl_or_b32 v152, v2, 12, v5
	global_load_lds_dwordx4 v146, s[18:19]
	s_mov_b32 m0, s9
	s_add_u32 s18, s12, 0x80000
	global_load_lds_dwordx4 v152, s[12:13]
	s_mov_b32 m0, s55
	s_addc_u32 s19, s13, 0
	s_add_i32 s56, s9, 0x4000
	global_load_lds_dwordx4 v148, s[12:13]
	s_mov_b32 m0, s56
	s_add_i32 s57, s9, 0x6000
	global_load_lds_dwordx4 v152, s[18:19]
	s_mov_b32 m0, s57
	v_mov_b32_e32 v151, 0
	global_load_lds_dwordx4 v148, s[18:19]
	s_load_dwordx2 s[42:43], s[4:5], 0xb0
	s_load_dwordx2 s[38:39], s[6:7], 0xb0
	s_load_dwordx2 s[44:45], s[22:23], 0xb8
	s_nop 0
	s_load_dwordx2 s[6:7], s[24:25], 0xb8
	s_load_dwordx2 s[4:5], s[26:27], 0xb8
	s_load_dwordx2 s[22:23], s[28:29], 0xb8
	s_load_dwordx2 s[40:41], s[30:31], 0xb8
	s_nop 0
	s_load_dwordx2 s[34:35], s[34:35], 0xb8
	s_nop 0
	s_load_dwordx2 s[30:31], s[36:37], 0xb8
	v_mov_b32_e32 v147, v151
	v_mov_b32_e32 v153, v151
	v_mov_b32_e32 v149, v151
	s_cmp_eq_u32 s15, 1
	s_mov_b32 s58, 0
	v_lshl_add_u64 v[8:9], s[10:11], 0, v[150:151]
	v_lshl_add_u64 v[6:7], s[10:11], 0, v[146:147]
	v_lshl_add_u64 v[2:3], s[12:13], 0, v[152:153]
	s_cselect_b64 s[24:25], -1, 0
	s_cmp_lg_u32 s15, 1
	v_lshl_add_u64 v[4:5], s[12:13], 0, v[148:149]
	s_cbranch_scc1 .LBB0_1493
	s_barrier

.LBB0_1594:
	.p2alignl 8, 3212836864
	s_nop 0
	s_nop 0
	s_nop 0
	s_nop 0
	s_nop 0
	s_nop 0
	s_nop 0
	s_nop 0
	s_nop 0
	s_nop 0
	s_nop 0
	s_nop 0
	s_nop 0
	s_nop 0
	s_cmp_lt_i32 s84, 24
	s_cselect_b64 s[4:5], -1, 0
	s_cmp_gt_i32 s85, 23
	s_cselect_b64 s[6:7], -1, 0
	s_and_b64 s[4:5], s[4:5], s[6:7]
	s_andn2_b64 vcc, exec, s[4:5]
	s_cbranch_vccnz .LBB0_1665
	s_mov_b64 s[6:7], s[70:71]
	s_mov_b64 s[8:9], s[70:71]
	s_mov_b64 s[4:5], s[70:71]
	s_cmpk_gt_i32 s2, 0xaff
	v_readfirstlane_b32 s13, v0
	s_cbranch_scc1 .LBB0_1611
	s_load_dwordx2 s[10:11], s[6:7], 0xb8
	s_load_dwordx2 s[14:15], s[8:9], 0xb8
	v_lshrrev_b32_e32 v2, 5, v0
	v_lshrrev_b32_e32 v4, 1, v0
	v_and_b32_e32 v2, 4, v2
	v_bfe_u32 v3, v0, 2, 2
	v_and_b32_e32 v13, 24, v4
	s_waitcnt lgkmcnt(0)
	s_add_u32 s40, s10, 0x18000000
	v_or3_b32 v2, v2, v3, v13
	v_lshlrev_b32_e32 v3, 4, v0
	s_addc_u32 s41, s11, 0
	v_or_b32_e32 v10, 0x2000, v3
	s_add_u32 s42, s14, 0xa800000
	v_lshrrev_b32_e32 v4, 7, v10
	s_movk_i32 s0, 0x60
	s_addc_u32 s43, s15, 0
	v_and_or_b32 v5, v4, s0, v2
	v_bfe_u32 v14, v0, 2, 4
	s_movk_i32 s0, 0x70
	s_ashr_i32 s45, s2, 31
	v_and_or_b32 v4, v4, s0, v14
	s_lshr_b32 s0, s45, 29
	s_add_i32 s0, s2, s0
	s_lshr_b32 s3, s13, 6
	s_ashr_i32 s1, s0, 3
	s_and_b32 s0, s0, -8
	s_lshr_b32 s14, s13, 8
	s_lshl_b32 s44, s3, 10
	s_sub_i32 s0, s2, s0
	s_cmp_lt_i32 s0, 0
	s_movk_i32 s46, 0x161
	s_cselect_b32 s6, s46, 0x160
	s_mul_i32 s0, s0, s6
	s_add_i32 s0, s0, s1
	s_mul_hi_i32 s1, s0, 0x2e8ba2e9
	s_lshr_b32 s6, s1, 31
	s_ashr_i32 s1, s1, 6
	s_add_i32 s1, s1, s6
	s_lshl_b32 s7, s1, 3
	s_mulk_i32 s1, 0x160
	s_sub_i32 s0, s0, s1
	s_bfe_u32 s1, s0, 0x3001c
	s_add_i32 s1, s0, s1
	s_sext_i32_i16 s6, s1
	s_and_b32 s1, s1, 0xfff8
	s_sub_i32 s0, s0, s1
	s_sext_i32_i16 s0, s0
	v_and_b32_e32 v6, 32, v0
	s_lshr_b32 s12, s6, 3
	s_add_i32 s30, s7, s0
	v_bitop3_b32 v11, v3, v6, 48 bitop3:0x6c
	v_and_b32_e32 v12, 64, v0
	s_ashr_i32 s31, s30, 31
	s_bfe_i64 s[8:9], s[12:13], 0x100000
	v_or_b32_e32 v3, v11, v12
	s_lshl_b64 s[6:7], s[30:31], 20
	s_lshl_b64 s[8:9], s[8:9], 20
	v_lshl_or_b32 v132, v4, 12, v3
	v_lshrrev_b32_e32 v4, 3, v0
	s_add_u32 s36, s42, s8
	v_and_or_b32 v2, v4, 32, v2
	s_addc_u32 s37, s43, s9
	s_add_i32 s31, s44, 0
	v_lshl_or_b32 v134, v2, 12, v3
	s_add_i32 m0, s31, 0x10000
	v_lshl_or_b32 v130, v5, 12, v3
	global_load_lds_dwordx4 v134, s[36:37]
	s_add_i32 m0, s31, 0x12000
	s_add_u32 s8, s36, 0x80000
	global_load_lds_dwordx4 v130, s[36:37]
	s_addc_u32 s9, s37, 0
	s_add_i32 m0, s31, 0x14000
	v_and_or_b32 v2, v4, 48, v14
	global_load_lds_dwordx4 v134, s[8:9]
	s_add_i32 m0, s31, 0x16000
	s_add_u32 s34, s40, s6
	s_addc_u32 s35, s41, s7
	s_add_i32 s47, s31, 0x2000
	v_lshl_or_b32 v136, v2, 12, v3
	global_load_lds_dwordx4 v130, s[8:9]
	s_mov_b32 m0, s31
	s_add_u32 s6, s34, 0x80000
	global_load_lds_dwordx4 v136, s[34:35]
	s_mov_b32 m0, s47
	s_addc_u32 s7, s35, 0
	s_add_i32 s48, s31, 0x4000
	global_load_lds_dwordx4 v132, s[34:35]
	s_mov_b32 m0, s48
	s_add_i32 s49, s31, 0x6000
	global_load_lds_dwordx4 v136, s[6:7]
	s_mov_b32 m0, s49
	s_load_dwordx2 s[4:5], s[4:5], 0xb8
	global_load_lds_dwordx4 v132, s[6:7]
	v_mov_b32_e32 v135, 0
	v_mov_b32_e32 v131, v135
	v_mov_b32_e32 v137, v135
	v_mov_b32_e32 v133, v135
	s_cmp_eq_u32 s14, 1
	s_mov_b32 s50, 0
	v_lshl_add_u64 v[8:9], s[36:37], 0, v[134:135]
	v_lshl_add_u64 v[6:7], s[36:37], 0, v[130:131]
	v_lshl_add_u64 v[2:3], s[34:35], 0, v[136:137]
	s_cselect_b64 s[6:7], -1, 0
	s_cmp_lg_u32 s14, 1
	v_lshl_add_u64 v[4:5], s[34:35], 0, v[132:133]
	s_cbranch_scc1 .LBB0_1598
	s_barrier

.LBB0_1665:
	.p2alignl 8, 3212836864
	s_nop 0
	s_nop 0
	s_nop 0
	s_nop 0
	s_nop 0
	s_nop 0
	s_nop 0
	s_nop 0
	s_cmp_lt_i32 s84, 25
	s_cselect_b64 s[4:5], -1, 0
	s_cmp_gt_i32 s85, 24
	s_cselect_b64 s[6:7], -1, 0
	s_and_b64 s[4:5], s[4:5], s[6:7]
	s_andn2_b64 vcc, exec, s[4:5]
	s_cbranch_vccnz .LBB0_1718
	s_and_b32 s0, s2, 7
	s_ashr_i32 s1, s33, 6
	s_mul_i32 s44, s1, s0
	s_ashr_i32 s0, s2, 6
	s_add_i32 s44, s44, s0
	s_mov_b64 s[4:5], s[70:71]
	s_mov_b64 s[6:7], s[70:71]
	s_mov_b64 s[8:9], s[70:71]
	s_mov_b64 s[10:11], s[70:71]
	s_mov_b64 s[12:13], s[70:71]
	s_mov_b64 s[18:19], s[70:71]
	s_mov_b64 s[14:15], s[70:71]
	s_mov_b64 s[20:21], s[70:71]
	s_cmp_gt_i32 s44, 63
	v_readfirstlane_b32 s36, v0
	s_cbranch_scc1 .LBB0_1718
	v_lshrrev_b32_e32 v2, 5, v0
	v_lshrrev_b32_e32 v4, 1, v0
	v_and_b32_e32 v2, 4, v2
	v_bfe_u32 v3, v0, 2, 2
	v_and_b32_e32 v4, 24, v4
	v_lshlrev_b32_e32 v188, 4, v0
	v_or3_b32 v2, v2, v3, v4
	v_bfe_u32 v3, v0, 3, 25
	s_waitcnt lgkmcnt(0)
	v_and_b32_e32 v5, 32, v0
	v_or_b32_e32 v3, 64, v3
	s_movk_i32 s0, 0x60
	v_bitop3_b32 v10, v188, v5, 48 bitop3:0x6c
	v_and_b32_e32 v11, 64, v0
	s_load_dwordx2 s[22:23], s[4:5], 0xb8
	s_load_dwordx2 s[16:17], s[6:7], 0xb8
	v_and_or_b32 v4, v3, s0, v2
	v_or_b32_e32 v5, v10, v11
	v_mul_u32_u24_e32 v4, 0x1600, v4
	v_lshrrev_b32_e32 v5, 1, v5
	v_or_b32_e32 v4, v4, v5
	v_lshlrev_b32_e32 v130, 1, v4
	v_bfe_u32 v4, v0, 2, 4
	s_movk_i32 s0, 0x70
	s_waitcnt lgkmcnt(0)
	s_add_u32 s45, s22, 0x20000000
	v_and_or_b32 v3, v3, s0, v4
	s_addc_u32 s46, s23, 0
	s_lshr_b32 s40, s36, 6
	s_bfe_u32 s37, s2, 0x30003
	v_mul_u32_u24_e32 v12, 0x1600, v3
	s_lshr_b32 s39, s36, 8
	s_lshl_b32 s47, s40, 10
	v_or_b32_e32 v3, v12, v5
	s_mul_i32 s38, s37, 0x2c0000
	v_lshlrev_b32_e32 v132, 1, v3
	v_lshrrev_b32_e32 v3, 3, v0
	s_add_u32 s2, s16, s38
	v_and_or_b32 v2, v3, 32, v2
	s_addc_u32 s3, s17, 0
	v_mul_u32_u24_e32 v2, 0x1600, v2
	s_add_u32 s4, s2, 0x11600000
	v_or_b32_e32 v2, v2, v5
	s_addc_u32 s5, s3, 0
	s_add_i32 s48, s47, 0
	v_lshlrev_b32_e32 v134, 1, v2
	s_add_i32 m0, s48, 0x10000
	v_and_or_b32 v2, v3, 48, v4
	global_load_lds_dwordx4 v134, s[4:5]
	s_add_i32 m0, s48, 0x12000
	s_add_u32 s2, s2, 0x11760000
	global_load_lds_dwordx4 v130, s[4:5]
	s_addc_u32 s3, s3, 0
	s_add_i32 m0, s48, 0x14000
	s_mul_i32 s1, s44, 0x2c0000
	global_load_lds_dwordx4 v134, s[2:3]
	s_add_i32 m0, s48, 0x16000
	v_mul_u32_u24_e32 v13, 0x1600, v2
	s_mul_hi_i32 s0, s44, 0x2c0000
	s_add_u32 s30, s45, s1
	v_or_b32_e32 v2, v5, v13
	s_addc_u32 s31, s46, s0
	s_add_i32 s49, s48, 0x2000
	v_lshlrev_b32_e32 v136, 1, v2
	global_load_lds_dwordx4 v130, s[2:3]
	s_mov_b32 m0, s48
	s_add_u32 s2, s30, 0x160000
	global_load_lds_dwordx4 v136, s[30:31]
	s_mov_b32 m0, s49
	s_addc_u32 s3, s31, 0
	s_add_i32 s50, s48, 0x4000
	global_load_lds_dwordx4 v132, s[30:31]
	s_mov_b32 m0, s50
	s_add_i32 s51, s48, 0x6000
	global_load_lds_dwordx4 v136, s[2:3]
	s_mov_b32 m0, s51
	v_mov_b32_e32 v135, 0
	global_load_lds_dwordx4 v132, s[2:3]
	s_load_dwordx2 s[26:27], s[8:9], 0xb0
	s_load_dwordx2 s[22:23], s[10:11], 0xb0
	s_load_dwordx2 s[28:29], s[12:13], 0xb8
	s_load_dwordx2 s[34:35], s[18:19], 0xb8
	s_load_dwordx2 s[2:3], s[14:15], 0xb8
	s_load_dwordx2 s[6:7], s[20:21], 0xb8
	s_load_dwordx2 s[24:25], s[70:71], 0xa8
	v_mov_b32_e32 v131, v135
	v_mov_b32_e32 v137, v135
	v_mov_b32_e32 v133, v135
	s_cmp_eq_u32 s39, 1
	s_mov_b32 s52, 0
	v_lshl_add_u64 v[8:9], s[4:5], 0, v[134:135]
	v_lshl_add_u64 v[6:7], s[4:5], 0, v[130:131]
	v_lshl_add_u64 v[4:5], s[30:31], 0, v[136:137]
	v_lshl_add_u64 v[2:3], s[30:31], 0, v[132:133]
	s_cselect_b64 s[8:9], -1, 0
	s_cmp_lg_u32 s39, 1
	s_mov_b64 s[10:11], 0x160000
	s_cbranch_scc1 .LBB0_1669
	s_barrier
